# bf16 GEMM epilogues (relu2/split) transposed through wave-private LDS scratch so each lane stores 16 B of a 128 B row segment (dwordx4) instead of 8 B scattered
# speedup vs baseline: 1.0302x; 1.0302x over previous
; template <class Epi>
; DI void gemm_tile(char* smem, const bf16_t* __restrict__ A0, int lda0, int ksplit, const bf16_t* __restrict__ A1, int lda1,
;                   const bf16_t* __restrict__ Bt, int K, int row0, int col0, const Epi& epi, int tid) {
;   constexpr int BK = 32, PITCH = 40, BUF = (256 + 128) * PITCH;
;   bf16_t* sbase = (bf16_t*)smem;
;   const int lane = tid & 63, wid = tid >> 6, wr = wid >> 1, wc = wid & 1, fr = lane & 15, fq = lane >> 4;
;   f32x4 acc[8][4];
; #pragma unroll
;   for (int m = 0; m < 8; ++m)
; #pragma unroll
;     for (int n = 0; n < 4; ++n) acc[m][n] = (f32x4){0.f, 0.f, 0.f, 0.f};
;   u32x4 ra[2][4], rb[2][2];
;   const int nk = K / BK;
;   const int sr = tid >> 2, scv = tid & 3;
; template <class Epi>
; DI void gemm_phase(char* smem, const bf16_t* A0, int lda0, int ksplit, const bf16_t* A1, int lda1, const bf16_t* Bt, int K, int nN, const Epi& epi, int tid) {
;   const int G = gridDim.x;
;   if ((G & 7) == 0) {
;     const int x = blockIdx.x & 7, l = blockIdx.x >> 3, L = G >> 3, per = 8 * nN, tot = 2 * per;
.LBB0_60:
	s_load_dwordx4 s[52:55], s[74:75], 0x160
	s_load_dwordx8 s[0:7], s[74:75], 0x140
	s_load_dwordx16 s[36:51], s[74:75], 0x80
	s_cmp_gt_i32 s94, 1
	v_mbcnt_lo_u32_b32 v194, -1, 0
	s_waitcnt lgkmcnt(0)
	v_writelane_b32 v253, s0, 48
	s_nop 1
	v_writelane_b32 v253, s1, 49
	v_writelane_b32 v253, s2, 50
	v_writelane_b32 v253, s3, 51
	v_writelane_b32 v253, s4, 52
	v_writelane_b32 v253, s5, 53
	v_writelane_b32 v253, s6, 54
	v_writelane_b32 v253, s7, 55
	s_cselect_b64 s[0:1], -1, 0
	s_cmp_lt_i32 s95, 2
	s_cselect_b64 s[2:3], -1, 0
	s_or_b64 s[0:1], s[0:1], s[2:3]
	s_and_b64 vcc, exec, s[0:1]
	s_cbranch_vccnz .LBB0_344
	s_load_dword s26, s[74:75], 0x180
	s_add_u32 s0, s92, 0x3800000
	s_addc_u32 s1, s93, 0
	s_and_b32 s28, s72, 0xffffffc0
	v_mbcnt_hi_u32_b32 v195, -1, v194
	s_waitcnt lgkmcnt(0)
	s_and_b32 s27, s26, 7
	s_cmp_lg_u32 s27, 0
	v_add_u32_e32 v196, s28, v195
	v_mbcnt_lo_u32_b32 v240, -1, 0
	v_mbcnt_hi_u32_b32 v240, -1, v240
	s_lshr_b32 s23, s72, 6
	s_lshl_b32 s100, s23, 10
	v_and_b32_e32 v241, 15, v240
	v_lshrrev_b32_e32 v242, 4, v240
	v_bfe_u32 v243, v240, 3, 1
	v_mul_u32_u24_e32 v243, 3, v243
	v_xor_b32_e32 v243, v242, v243
	v_lshlrev_b32_e32 v243, 4, v243
	v_lshl_add_u32 v243, v241, 6, v243
	s_lshr_b32 s22, s23, 1
	s_lshl_b32 s22, s22, 13
	v_add_u32_e32 v230, s22, v243
	s_and_b32 s22, s23, 1
	s_lshl_b32 s22, s22, 12
	s_add_u32 s22, s22, 16384
	v_add_u32_e32 v231, s22, v243
	s_lshr_b32 s22, s23, 1
	s_lshl_b32 s22, s22, 7
	v_add_u32_e32 v244, s22, v241
	s_and_b32 s22, s23, 1
	s_lshl_b32 s22, s22, 6
	v_lshl_add_u32 v245, v242, 2, s22
	s_movk_i32 s22, 3584
	v_mul_lo_u32 v246, v244, s22
	v_lshl_add_u32 v234, v245, 1, v246
	s_movk_i32 s22, 5184
	v_mul_lo_u32 v246, v244, s22
	v_lshl_add_u32 v235, v245, 1, v246
	s_mul_i32 s22, s23, 18432
	v_mul_u32_u24_e32 v246, 144, v241
	v_lshl_add_u32 v246, v242, 3, v246
	v_add_u32_e32 v236, s22, v246
	v_lshrrev_b32_e32 v246, 3, v240
	v_mul_u32_u24_e32 v246, 144, v246
	v_and_b32_e32 v247, 7, v240
	v_lshl_add_u32 v246, v247, 4, v246
	v_add_u32_e32 v237, s22, v246
	s_lshr_b32 s22, s23, 1
	s_lshl_b32 s22, s22, 7
	v_lshrrev_b32_e32 v246, 3, v240
	v_add_u32_e32 v246, s22, v246
	s_and_b32 s22, s23, 1
	s_lshl_b32 s22, s22, 6
	v_lshl_add_u32 v248, v247, 3, s22
	s_movk_i32 s22, 3584
	v_mul_lo_u32 v247, v246, s22
	v_lshl_add_u32 v238, v248, 1, v247
	s_movk_i32 s22, 5184
	v_mul_lo_u32 v247, v246, s22
	v_lshl_add_u32 v239, v248, 1, v247
	v_lshrrev_b32_e32 v241, 2, v240
	s_lshl_b32 s22, s23, 4
	v_add_u32_e32 v241, s22, v241
	v_bfe_u32 v242, v240, 5, 1
	v_mul_u32_u24_e32 v242, 3, v242
	v_and_b32_e32 v243, 3, v240
	v_xor_b32_e32 v243, v243, v242
	v_lshlrev_b32_e32 v243, 4, v243
	s_mov_b32 s22, 2048
	v_mad_u32_u24 v224, v241, s22, v243
	v_add_u32_e32 v225, 0x20000, v224
	v_add_u32_e32 v226, 0x40000, v224
	v_add_u32_e32 v227, 0x60000, v224
	s_mov_b32 s22, 2048
	v_mad_u32_u24 v228, v241, s22, v243
	v_add_u32_e32 v229, 0x20000, v228
	s_lshr_b32 s29, s96, 3
	s_and_b32 s101, s96, 7
	s_lshl_b32 s101, s101, 1
	s_waitcnt lgkmcnt(0)
; #define LWRITE(S, buf) do { bf16_t* sA_ = sbase + (buf) * BUF; bf16_t* sB_ = sA_ + 256 * PITCH; \
;     _Pragma("unroll") for (int i_ = 0; i_ < 4; ++i_) *(u32x4*)(sA_ + (sr + i_ * 64) * PITCH + scv * 8) = ra[S][i_]; \
;     _Pragma("unroll") for (int i_ = 0; i_ < 2; ++i_) *(u32x4*)(sB_ + (sr + i_ * 64) * PITCH + scv * 8) = rb[S][i_]; } while (0)
; template <class Epi>
; DI void gemm_tile(char* smem, const bf16_t* __restrict__ A0, int lda0, int ksplit, const bf16_t* __restrict__ A1, int lda1,
;                   const bf16_t* __restrict__ Bt, int K, int row0, int col0, const Epi& epi, int tid) {
;     ...
;   f32x4 acc[8][4];
; #pragma unroll
;   for (int m = 0; m < 8; ++m)
; #pragma unroll
;     for (int n = 0; n < 4; ++n) acc[m][n] = (f32x4){0.f, 0.f, 0.f, 0.f};
;   u32x4 ra[2][4], rb[2][2];
;   const int nk = K / BK;
;   const int sr = tid >> 2, scv = tid & 3;
;     ...
;   __syncthreads();
;   {
;     const int last = nk - 1;
;     GLOAD(0, 0);
;     __builtin_amdgcn_sched_barrier(0);
;     GLOAD(1, 1);
;     __builtin_amdgcn_sched_barrier(0);
;     LWRITE(0, 0);
;     __builtin_amdgcn_sched_barrier(0);
;     GLOAD(0, (2 < last ? 2 : last));
;     __builtin_amdgcn_sched_barrier(0);
;     __syncthreads();
; template <class Epi>
; DI void gemm_phase(char* smem, const bf16_t* A0, int lda0, int ksplit, const bf16_t* A1, int lda1, const bf16_t* Bt, int K, int nN, const Epi& epi, int tid) {
;     ...
;     const int x = blockIdx.x & 7, l = blockIdx.x >> 3, L = G >> 3, per = 8 * nN, tot = 2 * per;
;     for (int q = l; q < tot; q += L) { const int rgl = q / per, rem = q % per, ct = rem >> 3, rt = (x * 2 + rgl) * 8 + (rem & 7);
;       gemm_tile(smem, A0, lda0, ksplit, A1, lda1, Bt, K, rt * 256, ct * 128, epi, tid); }
.Lg1_tile:
	s_cmpk_ge_u32 s29, 560
	s_cbranch_scc1 .Lg1_done
	s_cmpk_ge_u32 s29, 280
	s_cselect_b32 s23, 1, 0
	s_cselect_b32 s22, 280, 0
	s_sub_u32 s22, s29, s22
	s_add_u32 s23, s23, s101
	s_lshl_b32 s23, s23, 3
	s_and_b32 s25, s22, 7
	s_add_u32 s25, s25, s23
	s_lshl_b32 s25, s25, 8
	s_lshr_b32 s24, s22, 3
	s_lshl_b32 s24, s24, 7
	s_mul_i32 s23, s25, 2048
	s_add_u32 s23, s23, 0x3800000
	s_add_u32 s0, s92, s23
	s_addc_u32 s1, s93, 0
	s_mul_i32 s23, s24, 2048
	s_add_u32 s23, s23, 0x0
	s_add_u32 s2, s92, s23
	s_addc_u32 s3, s93, 0
	s_waitcnt lgkmcnt(0)
	s_barrier
	s_mov_b32 s99, 0
	s_mov_b32 s30, 0
	s_add_u32 s22, s30, s100
	s_add_u32 m0, s22, 0
	s_nop 0
	global_load_lds_dwordx4 v224, s[0:1]
	s_add_u32 m0, s22, 4096
	s_nop 0
	global_load_lds_dwordx4 v225, s[0:1]
	s_add_u32 m0, s22, 8192
	s_nop 0
	global_load_lds_dwordx4 v226, s[0:1]
	s_add_u32 m0, s22, 12288
	s_nop 0
	global_load_lds_dwordx4 v227, s[0:1]
	s_add_u32 m0, s22, 16384
	s_nop 0
	global_load_lds_dwordx4 v228, s[2:3]
	s_add_u32 m0, s22, 20480
	s_nop 0
	global_load_lds_dwordx4 v229, s[2:3]
	s_add_u32 s0, s0, 64
	s_addc_u32 s1, s1, 0
	s_add_u32 s2, s2, 64
	s_addc_u32 s3, s3, 0
	s_add_u32 s99, s99, 1
	s_add_u32 s30, s30, 24576
	s_cmp_eq_u32 s30, 73728
	s_cselect_b32 s30, 0, s30
	s_add_u32 s22, s30, s100
	s_add_u32 m0, s22, 0
	s_nop 0
	global_load_lds_dwordx4 v224, s[0:1]
	s_add_u32 m0, s22, 4096
	s_nop 0
	global_load_lds_dwordx4 v225, s[0:1]
	s_add_u32 m0, s22, 8192
	s_nop 0
	global_load_lds_dwordx4 v226, s[0:1]
	s_add_u32 m0, s22, 12288
	s_nop 0
	global_load_lds_dwordx4 v227, s[0:1]
	s_add_u32 m0, s22, 16384
	s_nop 0
	global_load_lds_dwordx4 v228, s[2:3]
	s_add_u32 m0, s22, 20480
	s_nop 0
	global_load_lds_dwordx4 v229, s[2:3]
	s_add_u32 s0, s0, 64
	s_addc_u32 s1, s1, 0
	s_add_u32 s2, s2, 64
	s_addc_u32 s3, s3, 0
	s_add_u32 s99, s99, 1
	s_add_u32 s30, s30, 24576
	s_cmp_eq_u32 s30, 73728
	s_cselect_b32 s30, 0, s30
	s_add_u32 s22, s30, s100
	s_add_u32 m0, s22, 0
	s_nop 0
	global_load_lds_dwordx4 v224, s[0:1]
	s_add_u32 m0, s22, 4096
	s_nop 0
	global_load_lds_dwordx4 v225, s[0:1]
	s_add_u32 m0, s22, 8192
	s_nop 0
	global_load_lds_dwordx4 v226, s[0:1]
	s_add_u32 m0, s22, 12288
	s_nop 0
	global_load_lds_dwordx4 v227, s[0:1]
	s_add_u32 m0, s22, 16384
	s_nop 0
	global_load_lds_dwordx4 v228, s[2:3]
	s_add_u32 m0, s22, 20480
	s_nop 0
	global_load_lds_dwordx4 v229, s[2:3]
	s_add_u32 s0, s0, 64
	s_addc_u32 s1, s1, 0
	s_add_u32 s2, s2, 64
	s_addc_u32 s3, s3, 0
	s_add_u32 s99, s99, 1
	s_add_u32 s30, s30, 24576
	s_cmp_eq_u32 s30, 73728
	s_cselect_b32 s30, 0, s30
	v_mov_b32_e32 v0, 0
	v_mov_b32_e32 v1, 0
	v_mov_b32_e32 v2, 0
	v_mov_b32_e32 v3, 0
	v_mov_b32_e32 v4, 0
	v_mov_b32_e32 v5, 0
	v_mov_b32_e32 v6, 0
	v_mov_b32_e32 v7, 0
	v_mov_b32_e32 v8, 0
	v_mov_b32_e32 v9, 0
	v_mov_b32_e32 v10, 0
	v_mov_b32_e32 v11, 0
	v_mov_b32_e32 v12, 0
	v_mov_b32_e32 v13, 0
	v_mov_b32_e32 v14, 0
	v_mov_b32_e32 v15, 0
	v_mov_b32_e32 v16, 0
	v_mov_b32_e32 v17, 0
	v_mov_b32_e32 v18, 0
	v_mov_b32_e32 v19, 0
	v_mov_b32_e32 v20, 0
	v_mov_b32_e32 v21, 0
	v_mov_b32_e32 v22, 0
	v_mov_b32_e32 v23, 0
	v_mov_b32_e32 v24, 0
	v_mov_b32_e32 v25, 0
	v_mov_b32_e32 v26, 0
	v_mov_b32_e32 v27, 0
	v_mov_b32_e32 v28, 0
	v_mov_b32_e32 v29, 0
	v_mov_b32_e32 v30, 0
	v_mov_b32_e32 v31, 0
	v_mov_b32_e32 v32, 0
	v_mov_b32_e32 v33, 0
	v_mov_b32_e32 v34, 0
	v_mov_b32_e32 v35, 0
	v_mov_b32_e32 v36, 0
	v_mov_b32_e32 v37, 0
	v_mov_b32_e32 v38, 0
	v_mov_b32_e32 v39, 0
	v_mov_b32_e32 v40, 0
	v_mov_b32_e32 v41, 0
	v_mov_b32_e32 v42, 0
	v_mov_b32_e32 v43, 0
	v_mov_b32_e32 v44, 0
	v_mov_b32_e32 v45, 0
	v_mov_b32_e32 v46, 0
	v_mov_b32_e32 v47, 0
	v_mov_b32_e32 v48, 0
	v_mov_b32_e32 v49, 0
	v_mov_b32_e32 v50, 0
	v_mov_b32_e32 v51, 0
	v_mov_b32_e32 v52, 0
	v_mov_b32_e32 v53, 0
	v_mov_b32_e32 v54, 0
	v_mov_b32_e32 v55, 0
	v_mov_b32_e32 v56, 0
	v_mov_b32_e32 v57, 0
	v_mov_b32_e32 v58, 0
	v_mov_b32_e32 v59, 0
	v_mov_b32_e32 v60, 0
	v_mov_b32_e32 v61, 0
	v_mov_b32_e32 v62, 0
	v_mov_b32_e32 v63, 0
	v_mov_b32_e32 v64, 0
	v_mov_b32_e32 v65, 0
	v_mov_b32_e32 v66, 0
	v_mov_b32_e32 v67, 0
	v_mov_b32_e32 v68, 0
	v_mov_b32_e32 v69, 0
	v_mov_b32_e32 v70, 0
	v_mov_b32_e32 v71, 0
	v_mov_b32_e32 v72, 0
	v_mov_b32_e32 v73, 0
	v_mov_b32_e32 v74, 0
	v_mov_b32_e32 v75, 0
	v_mov_b32_e32 v76, 0
	v_mov_b32_e32 v77, 0
	v_mov_b32_e32 v78, 0
	v_mov_b32_e32 v79, 0
	v_mov_b32_e32 v80, 0
	v_mov_b32_e32 v81, 0
	v_mov_b32_e32 v82, 0
	v_mov_b32_e32 v83, 0
	v_mov_b32_e32 v84, 0
	v_mov_b32_e32 v85, 0
	v_mov_b32_e32 v86, 0
	v_mov_b32_e32 v87, 0
	v_mov_b32_e32 v88, 0
	v_mov_b32_e32 v89, 0
	v_mov_b32_e32 v90, 0
	v_mov_b32_e32 v91, 0
	v_mov_b32_e32 v92, 0
	v_mov_b32_e32 v93, 0
	v_mov_b32_e32 v94, 0
	v_mov_b32_e32 v95, 0
	v_mov_b32_e32 v96, 0
	v_mov_b32_e32 v97, 0
	v_mov_b32_e32 v98, 0
	v_mov_b32_e32 v99, 0
	v_mov_b32_e32 v100, 0
	v_mov_b32_e32 v101, 0
	v_mov_b32_e32 v102, 0
	v_mov_b32_e32 v103, 0
	v_mov_b32_e32 v104, 0
	v_mov_b32_e32 v105, 0
	v_mov_b32_e32 v106, 0
	v_mov_b32_e32 v107, 0
	v_mov_b32_e32 v108, 0
	v_mov_b32_e32 v109, 0
	v_mov_b32_e32 v110, 0
	v_mov_b32_e32 v111, 0
	v_mov_b32_e32 v112, 0
	v_mov_b32_e32 v113, 0
	v_mov_b32_e32 v114, 0
	v_mov_b32_e32 v115, 0
	v_mov_b32_e32 v116, 0
	v_mov_b32_e32 v117, 0
	v_mov_b32_e32 v118, 0
	v_mov_b32_e32 v119, 0
	v_mov_b32_e32 v120, 0
	v_mov_b32_e32 v121, 0
	v_mov_b32_e32 v122, 0
	v_mov_b32_e32 v123, 0
	v_mov_b32_e32 v124, 0
	v_mov_b32_e32 v125, 0
	v_mov_b32_e32 v126, 0
	v_mov_b32_e32 v127, 0
	s_mov_b32 s98, 0
	s_mov_b32 s31, 24576
	s_waitcnt vmcnt(12)
	s_barrier
	ds_read_b128 v[128:131], v231 offset:0
	ds_read_b128 v[132:135], v231 offset:1024
	ds_read_b128 v[136:139], v231 offset:2048
	ds_read_b128 v[140:143], v231 offset:3072
	ds_read_b128 v[144:147], v230 offset:0
	ds_read_b128 v[148:151], v230 offset:1024
	ds_read_b128 v[152:155], v230 offset:2048
	ds_read_b128 v[156:159], v230 offset:3072
	ds_read_b128 v[160:163], v230 offset:4096
	ds_read_b128 v[164:167], v230 offset:5120
	ds_read_b128 v[168:171], v230 offset:6144
	ds_read_b128 v[172:175], v230 offset:7168

; DI unsigned pack2(float lo, float hi) { const f32x2c v = {lo, hi}; return __builtin_bit_cast(unsigned, __builtin_convertvector(v, bf16x2c)); }
; template <class Epi>
; DI void gemm_tile(char* smem, const bf16_t* __restrict__ A0, int lda0, int ksplit, const bf16_t* __restrict__ A1, int lda1,
;                   const bf16_t* __restrict__ Bt, int K, int row0, int col0, const Epi& epi, int tid) {
;     ...
; #pragma unroll
;   for (int m = 0; m < 8; ++m)
; #pragma unroll
;     for (int n = 0; n < 4; ++n) epi(row0 + wr * 128 + m * 16 + fr, col0 + wc * 64 + n * 16 + fq * 4, acc[m][n]);
; DI void st_bf16x4(bf16_t* o, f32x4 v) { u32x2 q; q.x = pack2(v[0], v[1]); q.y = pack2(v[2], v[3]); *(u32x2*)o = q; }
;   DI void operator()(int row, int col, f32x4 v) const {
;     if (col < n0) st_bf16x4(o0 + (size_t)row * ld0 + col, v);
;     else { const int c = col - n0; if (c < n1) st_bf16x4(o1 + (size_t)row * ld1 + c, v); }
;   }
.Lg1_epi:
	s_nop 7
	s_nop 7
	s_cmpk_ge_u32 s24, 1792
	s_cbranch_scc1 .Lg1_eo1
	s_mul_i32 s23, s25, 3584
	s_lshl_b32 s22, s24, 1
	s_add_u32 s23, s23, s22
	s_add_u32 s23, s23, 0x7800000
	s_add_u32 s4, s92, s23
	s_addc_u32 s5, s93, 0
	v_cvt_pk_bf16_f32 v128, v0, v1
	v_cvt_pk_bf16_f32 v129, v2, v3
	ds_write_b64 v236, v[128:129]
	v_cvt_pk_bf16_f32 v130, v4, v5
	v_cvt_pk_bf16_f32 v131, v6, v7
	ds_write_b64 v236, v[130:131] offset:32
	v_cvt_pk_bf16_f32 v132, v8, v9
	v_cvt_pk_bf16_f32 v133, v10, v11
	ds_write_b64 v236, v[132:133] offset:64
	v_cvt_pk_bf16_f32 v134, v12, v13
	v_cvt_pk_bf16_f32 v135, v14, v15
	ds_write_b64 v236, v[134:135] offset:96
	v_cvt_pk_bf16_f32 v136, v16, v17
	v_cvt_pk_bf16_f32 v137, v18, v19
	ds_write_b64 v236, v[136:137] offset:2304
	v_cvt_pk_bf16_f32 v138, v20, v21
	v_cvt_pk_bf16_f32 v139, v22, v23
	ds_write_b64 v236, v[138:139] offset:2336
	v_cvt_pk_bf16_f32 v140, v24, v25
	v_cvt_pk_bf16_f32 v141, v26, v27
	ds_write_b64 v236, v[140:141] offset:2368
	v_cvt_pk_bf16_f32 v142, v28, v29
	v_cvt_pk_bf16_f32 v143, v30, v31
	ds_write_b64 v236, v[142:143] offset:2400
	v_cvt_pk_bf16_f32 v144, v32, v33
	v_cvt_pk_bf16_f32 v145, v34, v35
	ds_write_b64 v236, v[144:145] offset:4608
	v_cvt_pk_bf16_f32 v146, v36, v37
	v_cvt_pk_bf16_f32 v147, v38, v39
	ds_write_b64 v236, v[146:147] offset:4640
	v_cvt_pk_bf16_f32 v148, v40, v41
	v_cvt_pk_bf16_f32 v149, v42, v43
	ds_write_b64 v236, v[148:149] offset:4672
	v_cvt_pk_bf16_f32 v150, v44, v45
	v_cvt_pk_bf16_f32 v151, v46, v47
	ds_write_b64 v236, v[150:151] offset:4704
	v_cvt_pk_bf16_f32 v152, v48, v49
	v_cvt_pk_bf16_f32 v153, v50, v51
	ds_write_b64 v236, v[152:153] offset:6912
	v_cvt_pk_bf16_f32 v154, v52, v53
	v_cvt_pk_bf16_f32 v155, v54, v55
	ds_write_b64 v236, v[154:155] offset:6944
	v_cvt_pk_bf16_f32 v156, v56, v57
	v_cvt_pk_bf16_f32 v157, v58, v59
	ds_write_b64 v236, v[156:157] offset:6976
	v_cvt_pk_bf16_f32 v158, v60, v61
	v_cvt_pk_bf16_f32 v159, v62, v63
	ds_write_b64 v236, v[158:159] offset:7008
	v_cvt_pk_bf16_f32 v128, v64, v65
	v_cvt_pk_bf16_f32 v129, v66, v67
	ds_write_b64 v236, v[128:129] offset:9216
	v_cvt_pk_bf16_f32 v130, v68, v69
	v_cvt_pk_bf16_f32 v131, v70, v71
	ds_write_b64 v236, v[130:131] offset:9248
	v_cvt_pk_bf16_f32 v132, v72, v73
	v_cvt_pk_bf16_f32 v133, v74, v75
	ds_write_b64 v236, v[132:133] offset:9280
	v_cvt_pk_bf16_f32 v134, v76, v77
	v_cvt_pk_bf16_f32 v135, v78, v79
	ds_write_b64 v236, v[134:135] offset:9312
	v_cvt_pk_bf16_f32 v136, v80, v81
	v_cvt_pk_bf16_f32 v137, v82, v83
	ds_write_b64 v236, v[136:137] offset:11520
	v_cvt_pk_bf16_f32 v138, v84, v85
	v_cvt_pk_bf16_f32 v139, v86, v87
	ds_write_b64 v236, v[138:139] offset:11552
	v_cvt_pk_bf16_f32 v140, v88, v89
	v_cvt_pk_bf16_f32 v141, v90, v91
	ds_write_b64 v236, v[140:141] offset:11584
	v_cvt_pk_bf16_f32 v142, v92, v93
	v_cvt_pk_bf16_f32 v143, v94, v95
	ds_write_b64 v236, v[142:143] offset:11616
	v_cvt_pk_bf16_f32 v144, v96, v97
	v_cvt_pk_bf16_f32 v145, v98, v99
	ds_write_b64 v236, v[144:145] offset:13824
	v_cvt_pk_bf16_f32 v146, v100, v101
	v_cvt_pk_bf16_f32 v147, v102, v103
	ds_write_b64 v236, v[146:147] offset:13856
	v_cvt_pk_bf16_f32 v148, v104, v105
	v_cvt_pk_bf16_f32 v149, v106, v107
	ds_write_b64 v236, v[148:149] offset:13888
	v_cvt_pk_bf16_f32 v150, v108, v109
	v_cvt_pk_bf16_f32 v151, v110, v111
	ds_write_b64 v236, v[150:151] offset:13920
	v_cvt_pk_bf16_f32 v152, v112, v113
	v_cvt_pk_bf16_f32 v153, v114, v115
	ds_write_b64 v236, v[152:153] offset:16128
	v_cvt_pk_bf16_f32 v154, v116, v117
	v_cvt_pk_bf16_f32 v155, v118, v119
	ds_write_b64 v236, v[154:155] offset:16160
	v_cvt_pk_bf16_f32 v156, v120, v121
	v_cvt_pk_bf16_f32 v157, v122, v123
	ds_write_b64 v236, v[156:157] offset:16192
	v_cvt_pk_bf16_f32 v158, v124, v125
	v_cvt_pk_bf16_f32 v159, v126, v127
	ds_write_b64 v236, v[158:159] offset:16224
	s_waitcnt lgkmcnt(0)
	ds_read_b128 v[128:131], v237
	ds_read_b128 v[132:135], v237 offset:1152
	ds_read_b128 v[136:139], v237 offset:2304
	ds_read_b128 v[140:143], v237 offset:3456
	ds_read_b128 v[144:147], v237 offset:4608
	ds_read_b128 v[148:151], v237 offset:5760
	ds_read_b128 v[152:155], v237 offset:6912
	ds_read_b128 v[156:159], v237 offset:8064
	ds_read_b128 v[160:163], v237 offset:9216
	ds_read_b128 v[164:167], v237 offset:10368
	ds_read_b128 v[168:171], v237 offset:11520
	ds_read_b128 v[172:175], v237 offset:12672
	ds_read_b128 v[176:179], v237 offset:13824
	ds_read_b128 v[180:183], v237 offset:14976
	ds_read_b128 v[184:187], v237 offset:16128
	ds_read_b128 v[188:191], v237 offset:17280
	s_waitcnt lgkmcnt(15)
	global_store_dwordx4 v238, v[128:131], s[4:5]
	s_add_u32 s4, s4, 0x7000
	s_addc_u32 s5, s5, 0
	s_waitcnt lgkmcnt(14)
	global_store_dwordx4 v238, v[132:135], s[4:5]
	s_add_u32 s4, s4, 0x7000
	s_addc_u32 s5, s5, 0
	s_waitcnt lgkmcnt(13)
	global_store_dwordx4 v238, v[136:139], s[4:5]
	s_add_u32 s4, s4, 0x7000
	s_addc_u32 s5, s5, 0
	s_waitcnt lgkmcnt(12)
	global_store_dwordx4 v238, v[140:143], s[4:5]
	s_add_u32 s4, s4, 0x7000
	s_addc_u32 s5, s5, 0
	s_waitcnt lgkmcnt(11)
	global_store_dwordx4 v238, v[144:147], s[4:5]
	s_add_u32 s4, s4, 0x7000
	s_addc_u32 s5, s5, 0
	s_waitcnt lgkmcnt(10)
	global_store_dwordx4 v238, v[148:151], s[4:5]
	s_add_u32 s4, s4, 0x7000
	s_addc_u32 s5, s5, 0
	s_waitcnt lgkmcnt(9)
	global_store_dwordx4 v238, v[152:155], s[4:5]
	s_add_u32 s4, s4, 0x7000
	s_addc_u32 s5, s5, 0
	s_waitcnt lgkmcnt(8)
	global_store_dwordx4 v238, v[156:159], s[4:5]
	s_add_u32 s4, s4, 0x7000
	s_addc_u32 s5, s5, 0
	s_waitcnt lgkmcnt(7)
	global_store_dwordx4 v238, v[160:163], s[4:5]
	s_add_u32 s4, s4, 0x7000
	s_addc_u32 s5, s5, 0
	s_waitcnt lgkmcnt(6)
	global_store_dwordx4 v238, v[164:167], s[4:5]
	s_add_u32 s4, s4, 0x7000
	s_addc_u32 s5, s5, 0
	s_waitcnt lgkmcnt(5)
	global_store_dwordx4 v238, v[168:171], s[4:5]
	s_add_u32 s4, s4, 0x7000
	s_addc_u32 s5, s5, 0
	s_waitcnt lgkmcnt(4)
	global_store_dwordx4 v238, v[172:175], s[4:5]
	s_add_u32 s4, s4, 0x7000
	s_addc_u32 s5, s5, 0
	s_waitcnt lgkmcnt(3)
	global_store_dwordx4 v238, v[176:179], s[4:5]
	s_add_u32 s4, s4, 0x7000
	s_addc_u32 s5, s5, 0
	s_waitcnt lgkmcnt(2)
	global_store_dwordx4 v238, v[180:183], s[4:5]
	s_add_u32 s4, s4, 0x7000
	s_addc_u32 s5, s5, 0
	s_waitcnt lgkmcnt(1)
	global_store_dwordx4 v238, v[184:187], s[4:5]
	s_add_u32 s4, s4, 0x7000
	s_addc_u32 s5, s5, 0
	s_waitcnt lgkmcnt(0)
	global_store_dwordx4 v238, v[188:191], s[4:5]
	s_nop 1
	s_branch .Lg1_enext
; DI unsigned pack2(float lo, float hi) { const f32x2c v = {lo, hi}; return __builtin_bit_cast(unsigned, __builtin_convertvector(v, bf16x2c)); }
; template <class Epi>
; DI void gemm_tile(char* smem, const bf16_t* __restrict__ A0, int lda0, int ksplit, const bf16_t* __restrict__ A1, int lda1,
;                   const bf16_t* __restrict__ Bt, int K, int row0, int col0, const Epi& epi, int tid) {
;     ...
; #pragma unroll
;   for (int m = 0; m < 8; ++m)
; #pragma unroll
;     for (int n = 0; n < 4; ++n) epi(row0 + wr * 128 + m * 16 + fr, col0 + wc * 64 + n * 16 + fq * 4, acc[m][n]);
; DI void st_bf16x4(bf16_t* o, f32x4 v) { u32x2 q; q.x = pack2(v[0], v[1]); q.y = pack2(v[2], v[3]); *(u32x2*)o = q; }
;   DI void operator()(int row, int col, f32x4 v) const {
;     if (col < n0) st_bf16x4(o0 + (size_t)row * ld0 + col, v);
;     else { const int c = col - n0; if (c < n1) st_bf16x4(o1 + (size_t)row * ld1 + c, v); }
;   }
.Lg1_eo1:
	s_mul_i32 s23, s25, 5184
	s_sub_u32 s22, s24, 1792
	s_lshl_b32 s22, s22, 1
	s_add_u32 s23, s23, s22
	s_add_u32 s23, s23, 0xe800000
	s_add_u32 s4, s92, s23
	s_addc_u32 s5, s93, 0
	v_cvt_pk_bf16_f32 v128, v0, v1
	v_cvt_pk_bf16_f32 v129, v2, v3
	ds_write_b64 v236, v[128:129]
	v_cvt_pk_bf16_f32 v130, v4, v5
	v_cvt_pk_bf16_f32 v131, v6, v7
	ds_write_b64 v236, v[130:131] offset:32
	v_cvt_pk_bf16_f32 v132, v8, v9
	v_cvt_pk_bf16_f32 v133, v10, v11
	ds_write_b64 v236, v[132:133] offset:64
	v_cvt_pk_bf16_f32 v134, v12, v13
	v_cvt_pk_bf16_f32 v135, v14, v15
	ds_write_b64 v236, v[134:135] offset:96
	v_cvt_pk_bf16_f32 v136, v16, v17
	v_cvt_pk_bf16_f32 v137, v18, v19
	ds_write_b64 v236, v[136:137] offset:2304
	v_cvt_pk_bf16_f32 v138, v20, v21
	v_cvt_pk_bf16_f32 v139, v22, v23
	ds_write_b64 v236, v[138:139] offset:2336
	v_cvt_pk_bf16_f32 v140, v24, v25
	v_cvt_pk_bf16_f32 v141, v26, v27
	ds_write_b64 v236, v[140:141] offset:2368
	v_cvt_pk_bf16_f32 v142, v28, v29
	v_cvt_pk_bf16_f32 v143, v30, v31
	ds_write_b64 v236, v[142:143] offset:2400
	v_cvt_pk_bf16_f32 v144, v32, v33
	v_cvt_pk_bf16_f32 v145, v34, v35
	ds_write_b64 v236, v[144:145] offset:4608
	v_cvt_pk_bf16_f32 v146, v36, v37
	v_cvt_pk_bf16_f32 v147, v38, v39
	ds_write_b64 v236, v[146:147] offset:4640
	v_cvt_pk_bf16_f32 v148, v40, v41
	v_cvt_pk_bf16_f32 v149, v42, v43
	ds_write_b64 v236, v[148:149] offset:4672
	v_cvt_pk_bf16_f32 v150, v44, v45
	v_cvt_pk_bf16_f32 v151, v46, v47
	ds_write_b64 v236, v[150:151] offset:4704
	v_cvt_pk_bf16_f32 v152, v48, v49
	v_cvt_pk_bf16_f32 v153, v50, v51
	ds_write_b64 v236, v[152:153] offset:6912
	v_cvt_pk_bf16_f32 v154, v52, v53
	v_cvt_pk_bf16_f32 v155, v54, v55
	ds_write_b64 v236, v[154:155] offset:6944
	v_cvt_pk_bf16_f32 v156, v56, v57
	v_cvt_pk_bf16_f32 v157, v58, v59
	ds_write_b64 v236, v[156:157] offset:6976
	v_cvt_pk_bf16_f32 v158, v60, v61
	v_cvt_pk_bf16_f32 v159, v62, v63
	ds_write_b64 v236, v[158:159] offset:7008
	v_cvt_pk_bf16_f32 v128, v64, v65
	v_cvt_pk_bf16_f32 v129, v66, v67
	ds_write_b64 v236, v[128:129] offset:9216
	v_cvt_pk_bf16_f32 v130, v68, v69
	v_cvt_pk_bf16_f32 v131, v70, v71
	ds_write_b64 v236, v[130:131] offset:9248
	v_cvt_pk_bf16_f32 v132, v72, v73
	v_cvt_pk_bf16_f32 v133, v74, v75
	ds_write_b64 v236, v[132:133] offset:9280
	v_cvt_pk_bf16_f32 v134, v76, v77
	v_cvt_pk_bf16_f32 v135, v78, v79
	ds_write_b64 v236, v[134:135] offset:9312
	v_cvt_pk_bf16_f32 v136, v80, v81
	v_cvt_pk_bf16_f32 v137, v82, v83
	ds_write_b64 v236, v[136:137] offset:11520
	v_cvt_pk_bf16_f32 v138, v84, v85
	v_cvt_pk_bf16_f32 v139, v86, v87
	ds_write_b64 v236, v[138:139] offset:11552
	v_cvt_pk_bf16_f32 v140, v88, v89
	v_cvt_pk_bf16_f32 v141, v90, v91
	ds_write_b64 v236, v[140:141] offset:11584
	v_cvt_pk_bf16_f32 v142, v92, v93
	v_cvt_pk_bf16_f32 v143, v94, v95
	ds_write_b64 v236, v[142:143] offset:11616
	v_cvt_pk_bf16_f32 v144, v96, v97
	v_cvt_pk_bf16_f32 v145, v98, v99
	ds_write_b64 v236, v[144:145] offset:13824
	v_cvt_pk_bf16_f32 v146, v100, v101
	v_cvt_pk_bf16_f32 v147, v102, v103
	ds_write_b64 v236, v[146:147] offset:13856
	v_cvt_pk_bf16_f32 v148, v104, v105
	v_cvt_pk_bf16_f32 v149, v106, v107
	ds_write_b64 v236, v[148:149] offset:13888
	v_cvt_pk_bf16_f32 v150, v108, v109
	v_cvt_pk_bf16_f32 v151, v110, v111
	ds_write_b64 v236, v[150:151] offset:13920
	v_cvt_pk_bf16_f32 v152, v112, v113
	v_cvt_pk_bf16_f32 v153, v114, v115
	ds_write_b64 v236, v[152:153] offset:16128
	v_cvt_pk_bf16_f32 v154, v116, v117
	v_cvt_pk_bf16_f32 v155, v118, v119
	ds_write_b64 v236, v[154:155] offset:16160
	v_cvt_pk_bf16_f32 v156, v120, v121
	v_cvt_pk_bf16_f32 v157, v122, v123
	ds_write_b64 v236, v[156:157] offset:16192
	v_cvt_pk_bf16_f32 v158, v124, v125
	v_cvt_pk_bf16_f32 v159, v126, v127
	ds_write_b64 v236, v[158:159] offset:16224
	s_waitcnt lgkmcnt(0)
	ds_read_b128 v[128:131], v237
	ds_read_b128 v[132:135], v237 offset:1152
	ds_read_b128 v[136:139], v237 offset:2304
	ds_read_b128 v[140:143], v237 offset:3456
	ds_read_b128 v[144:147], v237 offset:4608
	ds_read_b128 v[148:151], v237 offset:5760
	ds_read_b128 v[152:155], v237 offset:6912
	ds_read_b128 v[156:159], v237 offset:8064
	ds_read_b128 v[160:163], v237 offset:9216
	ds_read_b128 v[164:167], v237 offset:10368
	ds_read_b128 v[168:171], v237 offset:11520
	ds_read_b128 v[172:175], v237 offset:12672
	ds_read_b128 v[176:179], v237 offset:13824
	ds_read_b128 v[180:183], v237 offset:14976
	ds_read_b128 v[184:187], v237 offset:16128
	ds_read_b128 v[188:191], v237 offset:17280
	s_sub_u32 s22, s24, 1792
	s_sub_u32 s22, 2592, s22
	v_cmp_gt_i32_e32 vcc, s22, v248
	s_and_saveexec_b64 s[2:3], vcc
	s_waitcnt lgkmcnt(15)
	global_store_dwordx4 v239, v[128:131], s[4:5]
	s_add_u32 s4, s4, 0xa200
	s_addc_u32 s5, s5, 0
	s_waitcnt lgkmcnt(14)
	global_store_dwordx4 v239, v[132:135], s[4:5]
	s_add_u32 s4, s4, 0xa200
	s_addc_u32 s5, s5, 0
	s_waitcnt lgkmcnt(13)
	global_store_dwordx4 v239, v[136:139], s[4:5]
	s_add_u32 s4, s4, 0xa200
	s_addc_u32 s5, s5, 0
	s_waitcnt lgkmcnt(12)
	global_store_dwordx4 v239, v[140:143], s[4:5]
	s_add_u32 s4, s4, 0xa200
	s_addc_u32 s5, s5, 0
	s_waitcnt lgkmcnt(11)
	global_store_dwordx4 v239, v[144:147], s[4:5]
	s_add_u32 s4, s4, 0xa200
	s_addc_u32 s5, s5, 0
	s_waitcnt lgkmcnt(10)
	global_store_dwordx4 v239, v[148:151], s[4:5]
	s_add_u32 s4, s4, 0xa200
	s_addc_u32 s5, s5, 0
	s_waitcnt lgkmcnt(9)
	global_store_dwordx4 v239, v[152:155], s[4:5]
	s_add_u32 s4, s4, 0xa200
	s_addc_u32 s5, s5, 0
	s_waitcnt lgkmcnt(8)
	global_store_dwordx4 v239, v[156:159], s[4:5]
	s_add_u32 s4, s4, 0xa200
	s_addc_u32 s5, s5, 0
	s_waitcnt lgkmcnt(7)
	global_store_dwordx4 v239, v[160:163], s[4:5]
	s_add_u32 s4, s4, 0xa200
	s_addc_u32 s5, s5, 0
	s_waitcnt lgkmcnt(6)
	global_store_dwordx4 v239, v[164:167], s[4:5]
	s_add_u32 s4, s4, 0xa200
	s_addc_u32 s5, s5, 0
	s_waitcnt lgkmcnt(5)
	global_store_dwordx4 v239, v[168:171], s[4:5]
	s_add_u32 s4, s4, 0xa200
	s_addc_u32 s5, s5, 0
	s_waitcnt lgkmcnt(4)
	global_store_dwordx4 v239, v[172:175], s[4:5]
	s_add_u32 s4, s4, 0xa200
	s_addc_u32 s5, s5, 0
	s_waitcnt lgkmcnt(3)
	global_store_dwordx4 v239, v[176:179], s[4:5]
	s_add_u32 s4, s4, 0xa200
	s_addc_u32 s5, s5, 0
	s_waitcnt lgkmcnt(2)
	global_store_dwordx4 v239, v[180:183], s[4:5]
	s_add_u32 s4, s4, 0xa200
	s_addc_u32 s5, s5, 0
	s_waitcnt lgkmcnt(1)
	global_store_dwordx4 v239, v[184:187], s[4:5]
	s_add_u32 s4, s4, 0xa200
	s_addc_u32 s5, s5, 0
	s_waitcnt lgkmcnt(0)
	global_store_dwordx4 v239, v[188:191], s[4:5]
	s_or_b64 exec, exec, s[2:3]
	s_nop 1

; template <class Epi>
; DI void gemm_tile(char* smem, const bf16_t* __restrict__ A0, int lda0, int ksplit, const bf16_t* __restrict__ A1, int lda1,
;                   const bf16_t* __restrict__ Bt, int K, int row0, int col0, const Epi& epi, int tid) {
;   constexpr int BK = 32, PITCH = 40, BUF = (256 + 128) * PITCH;
;   bf16_t* sbase = (bf16_t*)smem;
;   const int lane = tid & 63, wid = tid >> 6, wr = wid >> 1, wc = wid & 1, fr = lane & 15, fq = lane >> 4;
;   f32x4 acc[8][4];
; #pragma unroll
;   for (int m = 0; m < 8; ++m)
; #pragma unroll
;     for (int n = 0; n < 4; ++n) acc[m][n] = (f32x4){0.f, 0.f, 0.f, 0.f};
;   u32x4 ra[2][4], rb[2][2];
;   const int nk = K / BK;
;   const int sr = tid >> 2, scv = tid & 3;
; template <class Epi>
; DI void gemm_phase(char* smem, const bf16_t* A0, int lda0, int ksplit, const bf16_t* A1, int lda1, const bf16_t* Bt, int K, int nN, const Epi& epi, int tid) {
;   const int G = gridDim.x;
;   if ((G & 7) == 0) {
;     const int x = blockIdx.x & 7, l = blockIdx.x >> 3, L = G >> 3, per = 8 * nN, tot = 2 * per;
.LBB0_901:
	s_cmp_gt_i32 s94, 8
	s_cselect_b64 s[0:1], -1, 0
	s_cmp_lt_i32 s95, 9
	s_cselect_b64 s[2:3], -1, 0
	s_or_b64 s[0:1], s[0:1], s[2:3]
	s_and_b64 vcc, exec, s[0:1]
	s_cbranch_vccnz .LBB0_929
	s_add_u32 s2, s92, 0x3800000
	s_waitcnt lgkmcnt(0)
	s_load_dword s14, s[74:75], 0x180
	s_addc_u32 s3, s93, 0
	s_add_u32 s4, s92, 0xbc0000
	s_addc_u32 s5, s93, 0
	s_add_u32 s0, s92, 0x7800000
	s_addc_u32 s1, s93, 0
	s_and_b32 s16, s72, 0xffffffc0
	v_mbcnt_hi_u32_b32 v195, -1, v194
	s_waitcnt lgkmcnt(0)
	s_and_b32 s15, s14, 7
	s_cmp_lg_u32 s15, 0
	s_waitcnt vmcnt(16)
	v_add_u32_e32 v196, s16, v195
	v_mbcnt_lo_u32_b32 v240, -1, 0
	v_mbcnt_hi_u32_b32 v240, -1, v240
	s_lshr_b32 s12, s72, 6
	s_lshl_b32 s101, s12, 10
	v_and_b32_e32 v241, 15, v240
	v_lshrrev_b32_e32 v242, 4, v240
	v_bfe_u32 v243, v240, 3, 1
	v_mul_u32_u24_e32 v243, 3, v243
	v_xor_b32_e32 v243, v242, v243
	v_lshlrev_b32_e32 v243, 4, v243
	v_lshl_add_u32 v243, v241, 6, v243
	s_lshr_b32 s11, s12, 1
	s_lshl_b32 s11, s11, 13
	v_add_u32_e32 v230, s11, v243
	s_and_b32 s11, s12, 1
	s_lshl_b32 s11, s11, 12
	s_add_u32 s11, s11, 16384
	v_add_u32_e32 v231, s11, v243
	s_lshr_b32 s11, s12, 1
	s_lshl_b32 s11, s11, 7
	v_add_u32_e32 v244, s11, v241
	s_and_b32 s11, s12, 1
	s_lshl_b32 s11, s11, 6
	v_lshl_add_u32 v245, v242, 2, s11
	s_movk_i32 s11, 0x2000
	v_mul_lo_u32 v246, v244, s11
	v_lshl_add_u32 v234, v245, 1, v246
	s_mul_i32 s11, s12, 18432
	v_mul_u32_u24_e32 v246, 144, v241
	v_lshl_add_u32 v246, v242, 3, v246
	v_add_u32_e32 v236, s11, v246
	v_lshrrev_b32_e32 v246, 3, v240
	v_mul_u32_u24_e32 v246, 144, v246
	v_and_b32_e32 v247, 7, v240
	v_lshl_add_u32 v246, v247, 4, v246
	v_add_u32_e32 v237, s11, v246
	s_lshr_b32 s11, s12, 1
	s_lshl_b32 s11, s11, 7
	v_lshrrev_b32_e32 v246, 3, v240
	v_add_u32_e32 v246, s11, v246
	s_and_b32 s11, s12, 1
	s_lshl_b32 s11, s11, 6
	v_lshl_add_u32 v248, v247, 3, s11
	s_movk_i32 s11, 8192
	v_mul_lo_u32 v247, v246, s11
	v_lshl_add_u32 v238, v248, 1, v247
	v_lshrrev_b32_e32 v241, 2, v240
	s_lshl_b32 s11, s12, 4
	v_add_u32_e32 v241, s11, v241
	v_bfe_u32 v242, v240, 5, 1
	v_mul_u32_u24_e32 v242, 3, v242
	v_and_b32_e32 v243, 3, v240
	v_xor_b32_e32 v243, v243, v242
	v_lshlrev_b32_e32 v243, 4, v243
	s_mov_b32 s11, 2048
	v_mad_u32_u24 v224, v241, s11, v243
	v_add_u32_e32 v225, 0x20000, v224
	v_add_u32_e32 v226, 0x40000, v224
	v_add_u32_e32 v227, 0x60000, v224
	s_mov_b32 s11, 2048
	v_mad_u32_u24 v228, v241, s11, v243
	v_add_u32_e32 v229, 0x20000, v228
	s_lshr_b32 s17, s96, 3
	s_and_b32 s20, s96, 7
	s_lshl_b32 s20, s20, 1
	s_waitcnt lgkmcnt(0)
; #define LWRITE(S, buf) do { bf16_t* sA_ = sbase + (buf) * BUF; bf16_t* sB_ = sA_ + 256 * PITCH; \
;     _Pragma("unroll") for (int i_ = 0; i_ < 4; ++i_) *(u32x4*)(sA_ + (sr + i_ * 64) * PITCH + scv * 8) = ra[S][i_]; \
;     _Pragma("unroll") for (int i_ = 0; i_ < 2; ++i_) *(u32x4*)(sB_ + (sr + i_ * 64) * PITCH + scv * 8) = rb[S][i_]; } while (0)
; template <class Epi>
; DI void gemm_tile(char* smem, const bf16_t* __restrict__ A0, int lda0, int ksplit, const bf16_t* __restrict__ A1, int lda1,
;                   const bf16_t* __restrict__ Bt, int K, int row0, int col0, const Epi& epi, int tid) {
;     ...
;   f32x4 acc[8][4];
; #pragma unroll
;   for (int m = 0; m < 8; ++m)
; #pragma unroll
;     for (int n = 0; n < 4; ++n) acc[m][n] = (f32x4){0.f, 0.f, 0.f, 0.f};
;   u32x4 ra[2][4], rb[2][2];
;   const int nk = K / BK;
;   const int sr = tid >> 2, scv = tid & 3;
;     ...
;   __syncthreads();
;   {
;     const int last = nk - 1;
;     GLOAD(0, 0);
;     __builtin_amdgcn_sched_barrier(0);
;     GLOAD(1, 1);
;     __builtin_amdgcn_sched_barrier(0);
;     LWRITE(0, 0);
;     __builtin_amdgcn_sched_barrier(0);
;     GLOAD(0, (2 < last ? 2 : last));
;     __builtin_amdgcn_sched_barrier(0);
;     __syncthreads();
; template <class Epi>
; DI void gemm_phase(char* smem, const bf16_t* A0, int lda0, int ksplit, const bf16_t* A1, int lda1, const bf16_t* Bt, int K, int nN, const Epi& epi, int tid) {
;     ...
;     const int x = blockIdx.x & 7, l = blockIdx.x >> 3, L = G >> 3, per = 8 * nN, tot = 2 * per;
;     for (int q = l; q < tot; q += L) { const int rgl = q / per, rem = q % per, ct = rem >> 3, rt = (x * 2 + rgl) * 8 + (rem & 7);
;       gemm_tile(smem, A0, lda0, ksplit, A1, lda1, Bt, K, rt * 256, ct * 128, epi, tid); }
.Lg8_tile:
	s_cmpk_ge_u32 s17, 512
	s_cbranch_scc1 .Lg8_done
	s_cmpk_ge_u32 s17, 256
	s_cselect_b32 s12, 1, 0
	s_cselect_b32 s11, 256, 0
	s_sub_u32 s11, s17, s11
	s_and_b32 s18, s11, 7
	s_lshl_b32 s18, s18, 3
	s_bfe_u32 s13, s11, 0x30003
	s_or_b32 s18, s18, s13
	s_andn2_b32 s11, s11, 63
	s_or_b32 s11, s11, s18
	s_add_u32 s12, s12, s20
	s_lshl_b32 s12, s12, 3
	s_and_b32 s18, s11, 7
	s_add_u32 s18, s18, s12
	s_lshl_b32 s18, s18, 8
	s_lshr_b32 s13, s11, 3
	s_lshl_b32 s13, s13, 7
	s_mul_i32 s12, s18, 2048
	s_add_u32 s12, s12, 0x3800000
	s_add_u32 s0, s92, s12
	s_addc_u32 s1, s93, 0
	s_mul_i32 s12, s13, 2048
	s_add_u32 s12, s12, 0xbc0000
	s_add_u32 s2, s92, s12
	s_addc_u32 s3, s93, 0
	s_waitcnt lgkmcnt(0)
	s_barrier
	s_mov_b32 s100, 0
	s_mov_b32 s19, 0
	s_add_u32 s11, s19, s101
	s_add_u32 m0, s11, 0
	s_nop 0
	global_load_lds_dwordx4 v224, s[0:1]
	s_add_u32 m0, s11, 4096
	s_nop 0
	global_load_lds_dwordx4 v225, s[0:1]
	s_add_u32 m0, s11, 8192
	s_nop 0
	global_load_lds_dwordx4 v226, s[0:1]
	s_add_u32 m0, s11, 12288
	s_nop 0
	global_load_lds_dwordx4 v227, s[0:1]
	s_add_u32 m0, s11, 16384
	s_nop 0
	global_load_lds_dwordx4 v228, s[2:3]
	s_add_u32 m0, s11, 20480
	s_nop 0
	global_load_lds_dwordx4 v229, s[2:3]
	s_add_u32 s0, s0, 64
	s_addc_u32 s1, s1, 0
	s_add_u32 s2, s2, 64
	s_addc_u32 s3, s3, 0
	s_add_u32 s100, s100, 1
	s_add_u32 s19, s19, 24576
	s_cmp_eq_u32 s19, 73728
	s_cselect_b32 s19, 0, s19
	s_add_u32 s11, s19, s101
	s_add_u32 m0, s11, 0
	s_nop 0
	global_load_lds_dwordx4 v224, s[0:1]
	s_add_u32 m0, s11, 4096
	s_nop 0
	global_load_lds_dwordx4 v225, s[0:1]
	s_add_u32 m0, s11, 8192
	s_nop 0
	global_load_lds_dwordx4 v226, s[0:1]
	s_add_u32 m0, s11, 12288
	s_nop 0
	global_load_lds_dwordx4 v227, s[0:1]
	s_add_u32 m0, s11, 16384
	s_nop 0
	global_load_lds_dwordx4 v228, s[2:3]
	s_add_u32 m0, s11, 20480
	s_nop 0
	global_load_lds_dwordx4 v229, s[2:3]
	s_add_u32 s0, s0, 64
	s_addc_u32 s1, s1, 0
	s_add_u32 s2, s2, 64
	s_addc_u32 s3, s3, 0
	s_add_u32 s100, s100, 1
	s_add_u32 s19, s19, 24576
	s_cmp_eq_u32 s19, 73728
	s_cselect_b32 s19, 0, s19
	s_add_u32 s11, s19, s101
	s_add_u32 m0, s11, 0
	s_nop 0
	global_load_lds_dwordx4 v224, s[0:1]
	s_add_u32 m0, s11, 4096
	s_nop 0
	global_load_lds_dwordx4 v225, s[0:1]
	s_add_u32 m0, s11, 8192
	s_nop 0
	global_load_lds_dwordx4 v226, s[0:1]
	s_add_u32 m0, s11, 12288
	s_nop 0
	global_load_lds_dwordx4 v227, s[0:1]
	s_add_u32 m0, s11, 16384
	s_nop 0
	global_load_lds_dwordx4 v228, s[2:3]
	s_add_u32 m0, s11, 20480
	s_nop 0
	global_load_lds_dwordx4 v229, s[2:3]
	s_add_u32 s0, s0, 64
	s_addc_u32 s1, s1, 0
	s_add_u32 s2, s2, 64
	s_addc_u32 s3, s3, 0
	s_add_u32 s100, s100, 1
	s_add_u32 s19, s19, 24576
	s_cmp_eq_u32 s19, 73728
	s_cselect_b32 s19, 0, s19
	v_mov_b32_e32 v0, 0
	v_mov_b32_e32 v1, 0
	v_mov_b32_e32 v2, 0
	v_mov_b32_e32 v3, 0
	v_mov_b32_e32 v4, 0
	v_mov_b32_e32 v5, 0
	v_mov_b32_e32 v6, 0
	v_mov_b32_e32 v7, 0
	v_mov_b32_e32 v8, 0
	v_mov_b32_e32 v9, 0
	v_mov_b32_e32 v10, 0
	v_mov_b32_e32 v11, 0
	v_mov_b32_e32 v12, 0
	v_mov_b32_e32 v13, 0
	v_mov_b32_e32 v14, 0
	v_mov_b32_e32 v15, 0
	v_mov_b32_e32 v16, 0
	v_mov_b32_e32 v17, 0
	v_mov_b32_e32 v18, 0
	v_mov_b32_e32 v19, 0
	v_mov_b32_e32 v20, 0
	v_mov_b32_e32 v21, 0
	v_mov_b32_e32 v22, 0
	v_mov_b32_e32 v23, 0
	v_mov_b32_e32 v24, 0
	v_mov_b32_e32 v25, 0
	v_mov_b32_e32 v26, 0
	v_mov_b32_e32 v27, 0
	v_mov_b32_e32 v28, 0
	v_mov_b32_e32 v29, 0
	v_mov_b32_e32 v30, 0
	v_mov_b32_e32 v31, 0
	v_mov_b32_e32 v32, 0
	v_mov_b32_e32 v33, 0
	v_mov_b32_e32 v34, 0
	v_mov_b32_e32 v35, 0
	v_mov_b32_e32 v36, 0
	v_mov_b32_e32 v37, 0
	v_mov_b32_e32 v38, 0
	v_mov_b32_e32 v39, 0
	v_mov_b32_e32 v40, 0
	v_mov_b32_e32 v41, 0
	v_mov_b32_e32 v42, 0
	v_mov_b32_e32 v43, 0
	v_mov_b32_e32 v44, 0
	v_mov_b32_e32 v45, 0
	v_mov_b32_e32 v46, 0
	v_mov_b32_e32 v47, 0
	v_mov_b32_e32 v48, 0
	v_mov_b32_e32 v49, 0
	v_mov_b32_e32 v50, 0
	v_mov_b32_e32 v51, 0
	v_mov_b32_e32 v52, 0
	v_mov_b32_e32 v53, 0
	v_mov_b32_e32 v54, 0
	v_mov_b32_e32 v55, 0
	v_mov_b32_e32 v56, 0
	v_mov_b32_e32 v57, 0
	v_mov_b32_e32 v58, 0
	v_mov_b32_e32 v59, 0
	v_mov_b32_e32 v60, 0
	v_mov_b32_e32 v61, 0
	v_mov_b32_e32 v62, 0
	v_mov_b32_e32 v63, 0
	v_mov_b32_e32 v64, 0
	v_mov_b32_e32 v65, 0
	v_mov_b32_e32 v66, 0
	v_mov_b32_e32 v67, 0
	v_mov_b32_e32 v68, 0
	v_mov_b32_e32 v69, 0
	v_mov_b32_e32 v70, 0
	v_mov_b32_e32 v71, 0
	v_mov_b32_e32 v72, 0
	v_mov_b32_e32 v73, 0
	v_mov_b32_e32 v74, 0
	v_mov_b32_e32 v75, 0
	v_mov_b32_e32 v76, 0
	v_mov_b32_e32 v77, 0
	v_mov_b32_e32 v78, 0
	v_mov_b32_e32 v79, 0
	v_mov_b32_e32 v80, 0
	v_mov_b32_e32 v81, 0
	v_mov_b32_e32 v82, 0
	v_mov_b32_e32 v83, 0
	v_mov_b32_e32 v84, 0
	v_mov_b32_e32 v85, 0
	v_mov_b32_e32 v86, 0
	v_mov_b32_e32 v87, 0
	v_mov_b32_e32 v88, 0
	v_mov_b32_e32 v89, 0
	v_mov_b32_e32 v90, 0
	v_mov_b32_e32 v91, 0
	v_mov_b32_e32 v92, 0
	v_mov_b32_e32 v93, 0
	v_mov_b32_e32 v94, 0
	v_mov_b32_e32 v95, 0
	v_mov_b32_e32 v96, 0
	v_mov_b32_e32 v97, 0
	v_mov_b32_e32 v98, 0
	v_mov_b32_e32 v99, 0
	v_mov_b32_e32 v100, 0
	v_mov_b32_e32 v101, 0
	v_mov_b32_e32 v102, 0
	v_mov_b32_e32 v103, 0
	v_mov_b32_e32 v104, 0
	v_mov_b32_e32 v105, 0
	v_mov_b32_e32 v106, 0
	v_mov_b32_e32 v107, 0
	v_mov_b32_e32 v108, 0
	v_mov_b32_e32 v109, 0
	v_mov_b32_e32 v110, 0
	v_mov_b32_e32 v111, 0
	v_mov_b32_e32 v112, 0
	v_mov_b32_e32 v113, 0
	v_mov_b32_e32 v114, 0
	v_mov_b32_e32 v115, 0
	v_mov_b32_e32 v116, 0
	v_mov_b32_e32 v117, 0
	v_mov_b32_e32 v118, 0
	v_mov_b32_e32 v119, 0
	v_mov_b32_e32 v120, 0
	v_mov_b32_e32 v121, 0
	v_mov_b32_e32 v122, 0
	v_mov_b32_e32 v123, 0
	v_mov_b32_e32 v124, 0
	v_mov_b32_e32 v125, 0
	v_mov_b32_e32 v126, 0
	v_mov_b32_e32 v127, 0
	s_mov_b32 s99, 0
	s_mov_b32 s98, 24576
	s_waitcnt vmcnt(12)
	s_barrier
	ds_read_b128 v[128:131], v231 offset:0
	ds_read_b128 v[132:135], v231 offset:1024
	ds_read_b128 v[136:139], v231 offset:2048
	ds_read_b128 v[140:143], v231 offset:3072
	ds_read_b128 v[144:147], v230 offset:0
	ds_read_b128 v[148:151], v230 offset:1024
	ds_read_b128 v[152:155], v230 offset:2048
	ds_read_b128 v[156:159], v230 offset:3072
	ds_read_b128 v[160:163], v230 offset:4096
	ds_read_b128 v[164:167], v230 offset:5120
	ds_read_b128 v[168:171], v230 offset:6144
	ds_read_b128 v[172:175], v230 offset:7168

; DI unsigned pack2(float lo, float hi) { const f32x2c v = {lo, hi}; return __builtin_bit_cast(unsigned, __builtin_convertvector(v, bf16x2c)); }
; template <class Epi>
; DI void gemm_tile(char* smem, const bf16_t* __restrict__ A0, int lda0, int ksplit, const bf16_t* __restrict__ A1, int lda1,
;                   const bf16_t* __restrict__ Bt, int K, int row0, int col0, const Epi& epi, int tid) {
;     ...
; #pragma unroll
;   for (int m = 0; m < 8; ++m)
; #pragma unroll
;     for (int n = 0; n < 4; ++n) epi(row0 + wr * 128 + m * 16 + fr, col0 + wc * 64 + n * 16 + fq * 4, acc[m][n]);
; }
; DI void st_bf16x4(bf16_t* o, f32x4 v) { u32x2 q; q.x = pack2(v[0], v[1]); q.y = pack2(v[2], v[3]); *(u32x2*)o = q; }
.Lg8_epi:
	s_nop 7
	s_nop 7
	s_mul_i32 s12, s18, 8192
	s_lshl_b32 s11, s13, 1
	s_add_u32 s12, s12, s11
	s_add_u32 s12, s12, 0x7800000
	s_add_u32 s4, s92, s12
	s_addc_u32 s5, s93, 0
	v_max_f32_e32 v0, 0, v0
	v_max_f32_e32 v1, 0, v1
	v_max_f32_e32 v2, 0, v2
	v_max_f32_e32 v3, 0, v3
	v_pk_mul_f32 v[0:1], v[0:1], v[0:1]
	v_pk_mul_f32 v[2:3], v[2:3], v[2:3]
	v_cvt_pk_bf16_f32 v128, v0, v1
	v_cvt_pk_bf16_f32 v129, v2, v3
	ds_write_b64 v236, v[128:129]
	v_max_f32_e32 v4, 0, v4
	v_max_f32_e32 v5, 0, v5
	v_max_f32_e32 v6, 0, v6
	v_max_f32_e32 v7, 0, v7
	v_pk_mul_f32 v[4:5], v[4:5], v[4:5]
	v_pk_mul_f32 v[6:7], v[6:7], v[6:7]
	v_cvt_pk_bf16_f32 v130, v4, v5
	v_cvt_pk_bf16_f32 v131, v6, v7
	ds_write_b64 v236, v[130:131] offset:32
	v_max_f32_e32 v8, 0, v8
	v_max_f32_e32 v9, 0, v9
	v_max_f32_e32 v10, 0, v10
	v_max_f32_e32 v11, 0, v11
	v_pk_mul_f32 v[8:9], v[8:9], v[8:9]
	v_pk_mul_f32 v[10:11], v[10:11], v[10:11]
	v_cvt_pk_bf16_f32 v132, v8, v9
	v_cvt_pk_bf16_f32 v133, v10, v11
	ds_write_b64 v236, v[132:133] offset:64
	v_max_f32_e32 v12, 0, v12
	v_max_f32_e32 v13, 0, v13
	v_max_f32_e32 v14, 0, v14
	v_max_f32_e32 v15, 0, v15
	v_pk_mul_f32 v[12:13], v[12:13], v[12:13]
	v_pk_mul_f32 v[14:15], v[14:15], v[14:15]
	v_cvt_pk_bf16_f32 v134, v12, v13
	v_cvt_pk_bf16_f32 v135, v14, v15
	ds_write_b64 v236, v[134:135] offset:96
	v_max_f32_e32 v16, 0, v16
	v_max_f32_e32 v17, 0, v17
	v_max_f32_e32 v18, 0, v18
	v_max_f32_e32 v19, 0, v19
	v_pk_mul_f32 v[16:17], v[16:17], v[16:17]
	v_pk_mul_f32 v[18:19], v[18:19], v[18:19]
	v_cvt_pk_bf16_f32 v136, v16, v17
	v_cvt_pk_bf16_f32 v137, v18, v19
	ds_write_b64 v236, v[136:137] offset:2304
	v_max_f32_e32 v20, 0, v20
	v_max_f32_e32 v21, 0, v21
	v_max_f32_e32 v22, 0, v22
	v_max_f32_e32 v23, 0, v23
	v_pk_mul_f32 v[20:21], v[20:21], v[20:21]
	v_pk_mul_f32 v[22:23], v[22:23], v[22:23]
	v_cvt_pk_bf16_f32 v138, v20, v21
	v_cvt_pk_bf16_f32 v139, v22, v23
	ds_write_b64 v236, v[138:139] offset:2336
	v_max_f32_e32 v24, 0, v24
	v_max_f32_e32 v25, 0, v25
	v_max_f32_e32 v26, 0, v26
	v_max_f32_e32 v27, 0, v27
	v_pk_mul_f32 v[24:25], v[24:25], v[24:25]
	v_pk_mul_f32 v[26:27], v[26:27], v[26:27]
	v_cvt_pk_bf16_f32 v140, v24, v25
	v_cvt_pk_bf16_f32 v141, v26, v27
	ds_write_b64 v236, v[140:141] offset:2368
	v_max_f32_e32 v28, 0, v28
	v_max_f32_e32 v29, 0, v29
	v_max_f32_e32 v30, 0, v30
	v_max_f32_e32 v31, 0, v31
	v_pk_mul_f32 v[28:29], v[28:29], v[28:29]
	v_pk_mul_f32 v[30:31], v[30:31], v[30:31]
	v_cvt_pk_bf16_f32 v142, v28, v29
	v_cvt_pk_bf16_f32 v143, v30, v31
	ds_write_b64 v236, v[142:143] offset:2400
	v_max_f32_e32 v32, 0, v32
	v_max_f32_e32 v33, 0, v33
	v_max_f32_e32 v34, 0, v34
	v_max_f32_e32 v35, 0, v35
	v_pk_mul_f32 v[32:33], v[32:33], v[32:33]
	v_pk_mul_f32 v[34:35], v[34:35], v[34:35]
	v_cvt_pk_bf16_f32 v144, v32, v33
	v_cvt_pk_bf16_f32 v145, v34, v35
	ds_write_b64 v236, v[144:145] offset:4608
	v_max_f32_e32 v36, 0, v36
	v_max_f32_e32 v37, 0, v37
	v_max_f32_e32 v38, 0, v38
	v_max_f32_e32 v39, 0, v39
	v_pk_mul_f32 v[36:37], v[36:37], v[36:37]
	v_pk_mul_f32 v[38:39], v[38:39], v[38:39]
	v_cvt_pk_bf16_f32 v146, v36, v37
	v_cvt_pk_bf16_f32 v147, v38, v39
	ds_write_b64 v236, v[146:147] offset:4640
	v_max_f32_e32 v40, 0, v40
	v_max_f32_e32 v41, 0, v41
	v_max_f32_e32 v42, 0, v42
	v_max_f32_e32 v43, 0, v43
	v_pk_mul_f32 v[40:41], v[40:41], v[40:41]
	v_pk_mul_f32 v[42:43], v[42:43], v[42:43]
	v_cvt_pk_bf16_f32 v148, v40, v41
	v_cvt_pk_bf16_f32 v149, v42, v43
	ds_write_b64 v236, v[148:149] offset:4672
	v_max_f32_e32 v44, 0, v44
	v_max_f32_e32 v45, 0, v45
	v_max_f32_e32 v46, 0, v46
	v_max_f32_e32 v47, 0, v47
	v_pk_mul_f32 v[44:45], v[44:45], v[44:45]
	v_pk_mul_f32 v[46:47], v[46:47], v[46:47]
	v_cvt_pk_bf16_f32 v150, v44, v45
	v_cvt_pk_bf16_f32 v151, v46, v47
	ds_write_b64 v236, v[150:151] offset:4704
	v_max_f32_e32 v48, 0, v48
	v_max_f32_e32 v49, 0, v49
	v_max_f32_e32 v50, 0, v50
	v_max_f32_e32 v51, 0, v51
	v_pk_mul_f32 v[48:49], v[48:49], v[48:49]
	v_pk_mul_f32 v[50:51], v[50:51], v[50:51]
	v_cvt_pk_bf16_f32 v152, v48, v49
	v_cvt_pk_bf16_f32 v153, v50, v51
	ds_write_b64 v236, v[152:153] offset:6912
	v_max_f32_e32 v52, 0, v52
	v_max_f32_e32 v53, 0, v53
	v_max_f32_e32 v54, 0, v54
	v_max_f32_e32 v55, 0, v55
	v_pk_mul_f32 v[52:53], v[52:53], v[52:53]
	v_pk_mul_f32 v[54:55], v[54:55], v[54:55]
	v_cvt_pk_bf16_f32 v154, v52, v53
	v_cvt_pk_bf16_f32 v155, v54, v55
	ds_write_b64 v236, v[154:155] offset:6944
	v_max_f32_e32 v56, 0, v56
	v_max_f32_e32 v57, 0, v57
	v_max_f32_e32 v58, 0, v58
	v_max_f32_e32 v59, 0, v59
	v_pk_mul_f32 v[56:57], v[56:57], v[56:57]
	v_pk_mul_f32 v[58:59], v[58:59], v[58:59]
	v_cvt_pk_bf16_f32 v156, v56, v57
	v_cvt_pk_bf16_f32 v157, v58, v59
	ds_write_b64 v236, v[156:157] offset:6976
	v_max_f32_e32 v60, 0, v60
	v_max_f32_e32 v61, 0, v61
	v_max_f32_e32 v62, 0, v62
	v_max_f32_e32 v63, 0, v63
	v_pk_mul_f32 v[60:61], v[60:61], v[60:61]
	v_pk_mul_f32 v[62:63], v[62:63], v[62:63]
	v_cvt_pk_bf16_f32 v158, v60, v61
	v_cvt_pk_bf16_f32 v159, v62, v63
	ds_write_b64 v236, v[158:159] offset:7008
	v_max_f32_e32 v64, 0, v64
	v_max_f32_e32 v65, 0, v65
	v_max_f32_e32 v66, 0, v66
	v_max_f32_e32 v67, 0, v67
	v_pk_mul_f32 v[64:65], v[64:65], v[64:65]
	v_pk_mul_f32 v[66:67], v[66:67], v[66:67]
	v_cvt_pk_bf16_f32 v128, v64, v65
	v_cvt_pk_bf16_f32 v129, v66, v67
	ds_write_b64 v236, v[128:129] offset:9216
	v_max_f32_e32 v68, 0, v68
	v_max_f32_e32 v69, 0, v69
	v_max_f32_e32 v70, 0, v70
	v_max_f32_e32 v71, 0, v71
	v_pk_mul_f32 v[68:69], v[68:69], v[68:69]
	v_pk_mul_f32 v[70:71], v[70:71], v[70:71]
	v_cvt_pk_bf16_f32 v130, v68, v69
	v_cvt_pk_bf16_f32 v131, v70, v71
	ds_write_b64 v236, v[130:131] offset:9248
	v_max_f32_e32 v72, 0, v72
	v_max_f32_e32 v73, 0, v73
; DI unsigned pack2(float lo, float hi) { const f32x2c v = {lo, hi}; return __builtin_bit_cast(unsigned, __builtin_convertvector(v, bf16x2c)); }
; template <class Epi>
; DI void gemm_tile(char* smem, const bf16_t* __restrict__ A0, int lda0, int ksplit, const bf16_t* __restrict__ A1, int lda1,
;                   const bf16_t* __restrict__ Bt, int K, int row0, int col0, const Epi& epi, int tid) {
;     ...
; #pragma unroll
;   for (int m = 0; m < 8; ++m)
; #pragma unroll
;     for (int n = 0; n < 4; ++n) epi(row0 + wr * 128 + m * 16 + fr, col0 + wc * 64 + n * 16 + fq * 4, acc[m][n]);
; }
; DI void st_bf16x4(bf16_t* o, f32x4 v) { u32x2 q; q.x = pack2(v[0], v[1]); q.y = pack2(v[2], v[3]); *(u32x2*)o = q; }
	v_max_f32_e32 v74, 0, v74
	v_max_f32_e32 v75, 0, v75
	v_pk_mul_f32 v[72:73], v[72:73], v[72:73]
	v_pk_mul_f32 v[74:75], v[74:75], v[74:75]
	v_cvt_pk_bf16_f32 v132, v72, v73
	v_cvt_pk_bf16_f32 v133, v74, v75
	ds_write_b64 v236, v[132:133] offset:9280
	v_max_f32_e32 v76, 0, v76
	v_max_f32_e32 v77, 0, v77
	v_max_f32_e32 v78, 0, v78
	v_max_f32_e32 v79, 0, v79
	v_pk_mul_f32 v[76:77], v[76:77], v[76:77]
	v_pk_mul_f32 v[78:79], v[78:79], v[78:79]
	v_cvt_pk_bf16_f32 v134, v76, v77
	v_cvt_pk_bf16_f32 v135, v78, v79
	ds_write_b64 v236, v[134:135] offset:9312
	v_max_f32_e32 v80, 0, v80
	v_max_f32_e32 v81, 0, v81
	v_max_f32_e32 v82, 0, v82
	v_max_f32_e32 v83, 0, v83
	v_pk_mul_f32 v[80:81], v[80:81], v[80:81]
	v_pk_mul_f32 v[82:83], v[82:83], v[82:83]
	v_cvt_pk_bf16_f32 v136, v80, v81
	v_cvt_pk_bf16_f32 v137, v82, v83
	ds_write_b64 v236, v[136:137] offset:11520
	v_max_f32_e32 v84, 0, v84
	v_max_f32_e32 v85, 0, v85
	v_max_f32_e32 v86, 0, v86
	v_max_f32_e32 v87, 0, v87
	v_pk_mul_f32 v[84:85], v[84:85], v[84:85]
	v_pk_mul_f32 v[86:87], v[86:87], v[86:87]
	v_cvt_pk_bf16_f32 v138, v84, v85
	v_cvt_pk_bf16_f32 v139, v86, v87
	ds_write_b64 v236, v[138:139] offset:11552
	v_max_f32_e32 v88, 0, v88
	v_max_f32_e32 v89, 0, v89
	v_max_f32_e32 v90, 0, v90
	v_max_f32_e32 v91, 0, v91
	v_pk_mul_f32 v[88:89], v[88:89], v[88:89]
	v_pk_mul_f32 v[90:91], v[90:91], v[90:91]
	v_cvt_pk_bf16_f32 v140, v88, v89
	v_cvt_pk_bf16_f32 v141, v90, v91
	ds_write_b64 v236, v[140:141] offset:11584
	v_max_f32_e32 v92, 0, v92
	v_max_f32_e32 v93, 0, v93
	v_max_f32_e32 v94, 0, v94
	v_max_f32_e32 v95, 0, v95
	v_pk_mul_f32 v[92:93], v[92:93], v[92:93]
	v_pk_mul_f32 v[94:95], v[94:95], v[94:95]
	v_cvt_pk_bf16_f32 v142, v92, v93
	v_cvt_pk_bf16_f32 v143, v94, v95
	ds_write_b64 v236, v[142:143] offset:11616
	v_max_f32_e32 v96, 0, v96
	v_max_f32_e32 v97, 0, v97
	v_max_f32_e32 v98, 0, v98
	v_max_f32_e32 v99, 0, v99
	v_pk_mul_f32 v[96:97], v[96:97], v[96:97]
	v_pk_mul_f32 v[98:99], v[98:99], v[98:99]
	v_cvt_pk_bf16_f32 v144, v96, v97
	v_cvt_pk_bf16_f32 v145, v98, v99
	ds_write_b64 v236, v[144:145] offset:13824
	v_max_f32_e32 v100, 0, v100
	v_max_f32_e32 v101, 0, v101
	v_max_f32_e32 v102, 0, v102
	v_max_f32_e32 v103, 0, v103
	v_pk_mul_f32 v[100:101], v[100:101], v[100:101]
	v_pk_mul_f32 v[102:103], v[102:103], v[102:103]
	v_cvt_pk_bf16_f32 v146, v100, v101
	v_cvt_pk_bf16_f32 v147, v102, v103
	ds_write_b64 v236, v[146:147] offset:13856
	v_max_f32_e32 v104, 0, v104
	v_max_f32_e32 v105, 0, v105
	v_max_f32_e32 v106, 0, v106
	v_max_f32_e32 v107, 0, v107
	v_pk_mul_f32 v[104:105], v[104:105], v[104:105]
	v_pk_mul_f32 v[106:107], v[106:107], v[106:107]
	v_cvt_pk_bf16_f32 v148, v104, v105
	v_cvt_pk_bf16_f32 v149, v106, v107
	ds_write_b64 v236, v[148:149] offset:13888
	v_max_f32_e32 v108, 0, v108
	v_max_f32_e32 v109, 0, v109
	v_max_f32_e32 v110, 0, v110
	v_max_f32_e32 v111, 0, v111
	v_pk_mul_f32 v[108:109], v[108:109], v[108:109]
	v_pk_mul_f32 v[110:111], v[110:111], v[110:111]
	v_cvt_pk_bf16_f32 v150, v108, v109
	v_cvt_pk_bf16_f32 v151, v110, v111
	ds_write_b64 v236, v[150:151] offset:13920
	v_max_f32_e32 v112, 0, v112
	v_max_f32_e32 v113, 0, v113
	v_max_f32_e32 v114, 0, v114
	v_max_f32_e32 v115, 0, v115
	v_pk_mul_f32 v[112:113], v[112:113], v[112:113]
	v_pk_mul_f32 v[114:115], v[114:115], v[114:115]
	v_cvt_pk_bf16_f32 v152, v112, v113
	v_cvt_pk_bf16_f32 v153, v114, v115
	ds_write_b64 v236, v[152:153] offset:16128
	v_max_f32_e32 v116, 0, v116
	v_max_f32_e32 v117, 0, v117
	v_max_f32_e32 v118, 0, v118
	v_max_f32_e32 v119, 0, v119
	v_pk_mul_f32 v[116:117], v[116:117], v[116:117]
	v_pk_mul_f32 v[118:119], v[118:119], v[118:119]
	v_cvt_pk_bf16_f32 v154, v116, v117
	v_cvt_pk_bf16_f32 v155, v118, v119
	ds_write_b64 v236, v[154:155] offset:16160
	v_max_f32_e32 v120, 0, v120
	v_max_f32_e32 v121, 0, v121
	v_max_f32_e32 v122, 0, v122
	v_max_f32_e32 v123, 0, v123
	v_pk_mul_f32 v[120:121], v[120:121], v[120:121]
	v_pk_mul_f32 v[122:123], v[122:123], v[122:123]
	v_cvt_pk_bf16_f32 v156, v120, v121
	v_cvt_pk_bf16_f32 v157, v122, v123
	ds_write_b64 v236, v[156:157] offset:16192
	v_max_f32_e32 v124, 0, v124
	v_max_f32_e32 v125, 0, v125
	v_max_f32_e32 v126, 0, v126
	v_max_f32_e32 v127, 0, v127
	v_pk_mul_f32 v[124:125], v[124:125], v[124:125]
	v_pk_mul_f32 v[126:127], v[126:127], v[126:127]
	v_cvt_pk_bf16_f32 v158, v124, v125
	v_cvt_pk_bf16_f32 v159, v126, v127
	ds_write_b64 v236, v[158:159] offset:16224
	s_waitcnt lgkmcnt(0)
	ds_read_b128 v[128:131], v237
	ds_read_b128 v[132:135], v237 offset:1152
	ds_read_b128 v[136:139], v237 offset:2304
	ds_read_b128 v[140:143], v237 offset:3456
	ds_read_b128 v[144:147], v237 offset:4608
	ds_read_b128 v[148:151], v237 offset:5760
	ds_read_b128 v[152:155], v237 offset:6912
	ds_read_b128 v[156:159], v237 offset:8064
	ds_read_b128 v[160:163], v237 offset:9216
	ds_read_b128 v[164:167], v237 offset:10368
	ds_read_b128 v[168:171], v237 offset:11520
	ds_read_b128 v[172:175], v237 offset:12672
	ds_read_b128 v[176:179], v237 offset:13824
	ds_read_b128 v[180:183], v237 offset:14976
	ds_read_b128 v[184:187], v237 offset:16128
	ds_read_b128 v[188:191], v237 offset:17280
	s_waitcnt lgkmcnt(15)
	global_store_dwordx4 v238, v[128:131], s[4:5]
	s_add_u32 s4, s4, 0x10000
	s_addc_u32 s5, s5, 0
	s_waitcnt lgkmcnt(14)
	global_store_dwordx4 v238, v[132:135], s[4:5]
	s_add_u32 s4, s4, 0x10000
	s_addc_u32 s5, s5, 0
	s_waitcnt lgkmcnt(13)
	global_store_dwordx4 v238, v[136:139], s[4:5]
	s_add_u32 s4, s4, 0x10000
	s_addc_u32 s5, s5, 0
	s_waitcnt lgkmcnt(12)
	global_store_dwordx4 v238, v[140:143], s[4:5]
	s_add_u32 s4, s4, 0x10000
	s_addc_u32 s5, s5, 0
	s_waitcnt lgkmcnt(11)
	global_store_dwordx4 v238, v[144:147], s[4:5]
	s_add_u32 s4, s4, 0x10000
	s_addc_u32 s5, s5, 0
	s_waitcnt lgkmcnt(10)
	global_store_dwordx4 v238, v[148:151], s[4:5]
	s_add_u32 s4, s4, 0x10000
	s_addc_u32 s5, s5, 0
	s_waitcnt lgkmcnt(9)
	global_store_dwordx4 v238, v[152:155], s[4:5]
	s_add_u32 s4, s4, 0x10000
	s_addc_u32 s5, s5, 0
	s_waitcnt lgkmcnt(8)
	global_store_dwordx4 v238, v[156:159], s[4:5]
	s_add_u32 s4, s4, 0x10000
	s_addc_u32 s5, s5, 0
	s_waitcnt lgkmcnt(7)
	global_store_dwordx4 v238, v[160:163], s[4:5]
	s_add_u32 s4, s4, 0x10000
	s_addc_u32 s5, s5, 0
	s_waitcnt lgkmcnt(6)
	global_store_dwordx4 v238, v[164:167], s[4:5]
	s_add_u32 s4, s4, 0x10000
	s_addc_u32 s5, s5, 0
	s_waitcnt lgkmcnt(5)
	global_store_dwordx4 v238, v[168:171], s[4:5]
	s_add_u32 s4, s4, 0x10000
	s_addc_u32 s5, s5, 0
	s_waitcnt lgkmcnt(4)
	global_store_dwordx4 v238, v[172:175], s[4:5]
	s_add_u32 s4, s4, 0x10000
	s_addc_u32 s5, s5, 0
	s_waitcnt lgkmcnt(3)
	global_store_dwordx4 v238, v[176:179], s[4:5]
	s_add_u32 s4, s4, 0x10000
	s_addc_u32 s5, s5, 0
	s_waitcnt lgkmcnt(2)
	global_store_dwordx4 v238, v[180:183], s[4:5]
	s_add_u32 s4, s4, 0x10000
	s_addc_u32 s5, s5, 0
	s_waitcnt lgkmcnt(1)
	global_store_dwordx4 v238, v[184:187], s[4:5]
	s_add_u32 s4, s4, 0x10000
	s_addc_u32 s5, s5, 0
	s_waitcnt lgkmcnt(0)
	global_store_dwordx4 v238, v[188:191], s[4:5]
	s_nop 1
	s_add_u32 s17, s17, 64
	s_branch .Lg8_tile

; #define PH(k) case k: if (ONLY_PHASE >= 0 && ONLY_PHASE != k) break;
; template <class Epi>
; DI void gemm_tile(char* smem, const bf16_t* __restrict__ A0, int lda0, int ksplit, const bf16_t* __restrict__ A1, int lda1,
;                   const bf16_t* __restrict__ Bt, int K, int row0, int col0, const Epi& epi, int tid) {
;   constexpr int BK = 32, PITCH = 40, BUF = (256 + 128) * PITCH;
;   bf16_t* sbase = (bf16_t*)smem;
;   const int lane = tid & 63, wid = tid >> 6, wr = wid >> 1, wc = wid & 1, fr = lane & 15, fq = lane >> 4;
;   f32x4 acc[8][4];
; #pragma unroll
;   for (int m = 0; m < 8; ++m)
; #pragma unroll
;     for (int n = 0; n < 4; ++n) acc[m][n] = (f32x4){0.f, 0.f, 0.f, 0.f};
;   u32x4 ra[2][4], rb[2][2];
;   const int nk = K / BK;
;   const int sr = tid >> 2, scv = tid & 3;
; template <int ph> DI void run_phase(const Ctx& c, char* smem) {
;     ...
;     PH(11) gemm_phase(smem, XN, 1024, 1 << 30, XN, 1024, (const bf16_t*)(ws + OFF_WCDIN), 1024, 21,
;                         EpiSplit{(bf16_t*)(ws + OFF_S5U), 512, 512, (bf16_t*)(ws + OFF_MLRAW), 2080, 2080}, TIDX); break;
.LBB0_975:
	s_cmp_gt_i32 s94, 11
	s_cselect_b64 s[0:1], -1, 0
	s_cmp_lt_i32 s95, 12
	s_cselect_b64 s[2:3], -1, 0
	s_or_b64 s[0:1], s[0:1], s[2:3]
	s_and_b64 vcc, exec, s[0:1]
	s_cbranch_vccnz .LBB0_1259
	s_load_dword s34, s[74:75], 0x180
	s_add_u32 s0, s92, 0x3800000
	s_addc_u32 s1, s93, 0
	s_add_u32 s10, s92, 0x2bc0000
	s_addc_u32 s11, s93, 0
	s_and_b32 s36, s72, 0xffffffc0
	v_mbcnt_hi_u32_b32 v195, -1, v194
	s_waitcnt lgkmcnt(0)
	s_and_b32 s35, s34, 7
	s_cmp_lg_u32 s35, 0
	s_waitcnt vmcnt(16)
	v_add_u32_e32 v196, s36, v195
	v_mbcnt_lo_u32_b32 v240, -1, 0
	v_mbcnt_hi_u32_b32 v240, -1, v240
	s_lshr_b32 s26, s72, 6
	s_lshl_b32 s99, s26, 10
	v_and_b32_e32 v241, 15, v240
	v_lshrrev_b32_e32 v242, 4, v240
	v_bfe_u32 v243, v240, 3, 1
	v_mul_u32_u24_e32 v243, 3, v243
	v_xor_b32_e32 v243, v242, v243
	v_lshlrev_b32_e32 v243, 4, v243
	v_lshl_add_u32 v243, v241, 6, v243
	s_lshr_b32 s25, s26, 1
	s_lshl_b32 s25, s25, 13
	v_add_u32_e32 v230, s25, v243
	s_and_b32 s25, s26, 1
	s_lshl_b32 s25, s25, 12
	s_add_u32 s25, s25, 16384
	v_add_u32_e32 v231, s25, v243
	s_lshr_b32 s25, s26, 1
	s_lshl_b32 s25, s25, 7
	v_add_u32_e32 v244, s25, v241
	s_and_b32 s25, s26, 1
	s_lshl_b32 s25, s25, 6
	v_lshl_add_u32 v245, v242, 2, s25
	s_movk_i32 s25, 1024
	v_mul_lo_u32 v246, v244, s25
	v_lshl_add_u32 v234, v245, 1, v246
	s_movk_i32 s25, 4160
	v_mul_lo_u32 v246, v244, s25
	v_lshl_add_u32 v235, v245, 1, v246
	s_mul_i32 s25, s26, 18432
	v_mul_u32_u24_e32 v246, 144, v241
	v_lshl_add_u32 v246, v242, 3, v246
	v_add_u32_e32 v236, s25, v246
	v_lshrrev_b32_e32 v246, 3, v240
	v_mul_u32_u24_e32 v246, 144, v246
	v_and_b32_e32 v247, 7, v240
	v_lshl_add_u32 v246, v247, 4, v246
	v_add_u32_e32 v237, s25, v246
	s_lshr_b32 s25, s26, 1
	s_lshl_b32 s25, s25, 7
	v_lshrrev_b32_e32 v246, 3, v240
	v_add_u32_e32 v246, s25, v246
	s_and_b32 s25, s26, 1
	s_lshl_b32 s25, s25, 6
	v_lshl_add_u32 v248, v247, 3, s25
	s_movk_i32 s25, 1024
	v_mul_lo_u32 v247, v246, s25
	v_lshl_add_u32 v238, v248, 1, v247
	s_movk_i32 s25, 4160
	v_mul_lo_u32 v247, v246, s25
	v_lshl_add_u32 v239, v248, 1, v247
	v_lshrrev_b32_e32 v241, 2, v240
	s_lshl_b32 s25, s26, 4
	v_add_u32_e32 v241, s25, v241
	v_bfe_u32 v242, v240, 5, 1
	v_mul_u32_u24_e32 v242, 3, v242
	v_and_b32_e32 v243, 3, v240
	v_xor_b32_e32 v243, v243, v242
	v_lshlrev_b32_e32 v243, 4, v243
	s_mov_b32 s25, 2048
	v_mad_u32_u24 v224, v241, s25, v243
	v_add_u32_e32 v225, 0x20000, v224
	v_add_u32_e32 v226, 0x40000, v224
	v_add_u32_e32 v227, 0x60000, v224
	s_mov_b32 s25, 2048
	v_mad_u32_u24 v228, v241, s25, v243
	v_add_u32_e32 v229, 0x20000, v228
	s_lshr_b32 s101, s96, 3
	s_and_b32 s100, s96, 7
	s_lshl_b32 s100, s100, 1
	s_waitcnt lgkmcnt(0)
; #define LWRITE(S, buf) do { bf16_t* sA_ = sbase + (buf) * BUF; bf16_t* sB_ = sA_ + 256 * PITCH; \
;     _Pragma("unroll") for (int i_ = 0; i_ < 4; ++i_) *(u32x4*)(sA_ + (sr + i_ * 64) * PITCH + scv * 8) = ra[S][i_]; \
;     _Pragma("unroll") for (int i_ = 0; i_ < 2; ++i_) *(u32x4*)(sB_ + (sr + i_ * 64) * PITCH + scv * 8) = rb[S][i_]; } while (0)
; template <class Epi>
; DI void gemm_tile(char* smem, const bf16_t* __restrict__ A0, int lda0, int ksplit, const bf16_t* __restrict__ A1, int lda1,
;                   const bf16_t* __restrict__ Bt, int K, int row0, int col0, const Epi& epi, int tid) {
;     ...
;   __syncthreads();
;   {
;     const int last = nk - 1;
;     GLOAD(0, 0);
;     __builtin_amdgcn_sched_barrier(0);
;     GLOAD(1, 1);
;     __builtin_amdgcn_sched_barrier(0);
;     LWRITE(0, 0);
;     __builtin_amdgcn_sched_barrier(0);
;     GLOAD(0, (2 < last ? 2 : last));
;     __builtin_amdgcn_sched_barrier(0);
;     __syncthreads();
; template <class Epi>
; DI void gemm_phase(char* smem, const bf16_t* A0, int lda0, int ksplit, const bf16_t* A1, int lda1, const bf16_t* Bt, int K, int nN, const Epi& epi, int tid) {
;     ...
;     const int x = blockIdx.x & 7, l = blockIdx.x >> 3, L = G >> 3, per = 8 * nN, tot = 2 * per;
;     for (int q = l; q < tot; q += L) { const int rgl = q / per, rem = q % per, ct = rem >> 3, rt = (x * 2 + rgl) * 8 + (rem & 7);
;       gemm_tile(smem, A0, lda0, ksplit, A1, lda1, Bt, K, rt * 256, ct * 128, epi, tid); }
.Lg11_tile:
	s_cmpk_ge_u32 s101, 336
	s_cbranch_scc1 .Lg11_done
	s_cmpk_ge_u32 s101, 168
	s_cselect_b32 s26, 1, 0
	s_cselect_b32 s25, 168, 0
	s_sub_u32 s25, s101, s25
	s_add_u32 s26, s26, s100
	s_lshl_b32 s26, s26, 3
	s_and_b32 s28, s25, 7
	s_add_u32 s28, s28, s26
	s_lshl_b32 s28, s28, 8
	s_lshr_b32 s27, s25, 3
	s_lshl_b32 s27, s27, 7
	s_mul_i32 s26, s28, 2048
	s_add_u32 s26, s26, 0x3800000
	s_add_u32 s0, s92, s26
	s_addc_u32 s1, s93, 0
	s_mul_i32 s26, s27, 2048
	s_add_u32 s26, s26, 0x2bc0000
	s_add_u32 s2, s92, s26
	s_addc_u32 s3, s93, 0
	s_waitcnt lgkmcnt(0)
	s_barrier
	s_mov_b32 s98, 0
	s_mov_b32 s29, 0
	s_add_u32 s25, s29, s99
	s_add_u32 m0, s25, 0
	s_nop 0
	global_load_lds_dwordx4 v224, s[0:1]
	s_add_u32 m0, s25, 4096
	s_nop 0
	global_load_lds_dwordx4 v225, s[0:1]
	s_add_u32 m0, s25, 8192
	s_nop 0
	global_load_lds_dwordx4 v226, s[0:1]
	s_add_u32 m0, s25, 12288
	s_nop 0
	global_load_lds_dwordx4 v227, s[0:1]
	s_add_u32 m0, s25, 16384
	s_nop 0
	global_load_lds_dwordx4 v228, s[2:3]
	s_add_u32 m0, s25, 20480
	s_nop 0
	global_load_lds_dwordx4 v229, s[2:3]
	s_add_u32 s0, s0, 64
	s_addc_u32 s1, s1, 0
	s_add_u32 s2, s2, 64
	s_addc_u32 s3, s3, 0
	s_add_u32 s98, s98, 1
	s_add_u32 s29, s29, 24576
	s_cmp_eq_u32 s29, 73728
	s_cselect_b32 s29, 0, s29
	s_add_u32 s25, s29, s99
	s_add_u32 m0, s25, 0
	s_nop 0
	global_load_lds_dwordx4 v224, s[0:1]
	s_add_u32 m0, s25, 4096
	s_nop 0
	global_load_lds_dwordx4 v225, s[0:1]
	s_add_u32 m0, s25, 8192
	s_nop 0
	global_load_lds_dwordx4 v226, s[0:1]
	s_add_u32 m0, s25, 12288
	s_nop 0
	global_load_lds_dwordx4 v227, s[0:1]
	s_add_u32 m0, s25, 16384
	s_nop 0
	global_load_lds_dwordx4 v228, s[2:3]
	s_add_u32 m0, s25, 20480
	s_nop 0
	global_load_lds_dwordx4 v229, s[2:3]
	s_add_u32 s0, s0, 64
	s_addc_u32 s1, s1, 0
	s_add_u32 s2, s2, 64
	s_addc_u32 s3, s3, 0
	s_add_u32 s98, s98, 1
	s_add_u32 s29, s29, 24576
	s_cmp_eq_u32 s29, 73728
	s_cselect_b32 s29, 0, s29
	s_add_u32 s25, s29, s99
	s_add_u32 m0, s25, 0
	s_nop 0
	global_load_lds_dwordx4 v224, s[0:1]
	s_add_u32 m0, s25, 4096
	s_nop 0
	global_load_lds_dwordx4 v225, s[0:1]
	s_add_u32 m0, s25, 8192
	s_nop 0
	global_load_lds_dwordx4 v226, s[0:1]
	s_add_u32 m0, s25, 12288
	s_nop 0
	global_load_lds_dwordx4 v227, s[0:1]
	s_add_u32 m0, s25, 16384
	s_nop 0
	global_load_lds_dwordx4 v228, s[2:3]
	s_add_u32 m0, s25, 20480
	s_nop 0
	global_load_lds_dwordx4 v229, s[2:3]
	s_add_u32 s0, s0, 64
	s_addc_u32 s1, s1, 0
	s_add_u32 s2, s2, 64
	s_addc_u32 s3, s3, 0
	s_add_u32 s98, s98, 1
	s_add_u32 s29, s29, 24576
	s_cmp_eq_u32 s29, 73728
	s_cselect_b32 s29, 0, s29
	v_mov_b32_e32 v0, 0
	v_mov_b32_e32 v1, 0
	v_mov_b32_e32 v2, 0
	v_mov_b32_e32 v3, 0
	v_mov_b32_e32 v4, 0
	v_mov_b32_e32 v5, 0
	v_mov_b32_e32 v6, 0
	v_mov_b32_e32 v7, 0
	v_mov_b32_e32 v8, 0
	v_mov_b32_e32 v9, 0
	v_mov_b32_e32 v10, 0
	v_mov_b32_e32 v11, 0
	v_mov_b32_e32 v12, 0
	v_mov_b32_e32 v13, 0
	v_mov_b32_e32 v14, 0
	v_mov_b32_e32 v15, 0
	v_mov_b32_e32 v16, 0
	v_mov_b32_e32 v17, 0
	v_mov_b32_e32 v18, 0
	v_mov_b32_e32 v19, 0
	v_mov_b32_e32 v20, 0
	v_mov_b32_e32 v21, 0
	v_mov_b32_e32 v22, 0
	v_mov_b32_e32 v23, 0
	v_mov_b32_e32 v24, 0
	v_mov_b32_e32 v25, 0
	v_mov_b32_e32 v26, 0
	v_mov_b32_e32 v27, 0
	v_mov_b32_e32 v28, 0
	v_mov_b32_e32 v29, 0
	v_mov_b32_e32 v30, 0
	v_mov_b32_e32 v31, 0
	v_mov_b32_e32 v32, 0
	v_mov_b32_e32 v33, 0
	v_mov_b32_e32 v34, 0
	v_mov_b32_e32 v35, 0
	v_mov_b32_e32 v36, 0
	v_mov_b32_e32 v37, 0
	v_mov_b32_e32 v38, 0
	v_mov_b32_e32 v39, 0
	v_mov_b32_e32 v40, 0
	v_mov_b32_e32 v41, 0
	v_mov_b32_e32 v42, 0
	v_mov_b32_e32 v43, 0
	v_mov_b32_e32 v44, 0
	v_mov_b32_e32 v45, 0
	v_mov_b32_e32 v46, 0
	v_mov_b32_e32 v47, 0
	v_mov_b32_e32 v48, 0
	v_mov_b32_e32 v49, 0
	v_mov_b32_e32 v50, 0
	v_mov_b32_e32 v51, 0
	v_mov_b32_e32 v52, 0
	v_mov_b32_e32 v53, 0
	v_mov_b32_e32 v54, 0
	v_mov_b32_e32 v55, 0
	v_mov_b32_e32 v56, 0
	v_mov_b32_e32 v57, 0
	v_mov_b32_e32 v58, 0
	v_mov_b32_e32 v59, 0
	v_mov_b32_e32 v60, 0
	v_mov_b32_e32 v61, 0
	v_mov_b32_e32 v62, 0
	v_mov_b32_e32 v63, 0
	v_mov_b32_e32 v64, 0
	v_mov_b32_e32 v65, 0
	v_mov_b32_e32 v66, 0
	v_mov_b32_e32 v67, 0
	v_mov_b32_e32 v68, 0
	v_mov_b32_e32 v69, 0
	v_mov_b32_e32 v70, 0
	v_mov_b32_e32 v71, 0
	v_mov_b32_e32 v72, 0
	v_mov_b32_e32 v73, 0
	v_mov_b32_e32 v74, 0
	v_mov_b32_e32 v75, 0
	v_mov_b32_e32 v76, 0
	v_mov_b32_e32 v77, 0
	v_mov_b32_e32 v78, 0
	v_mov_b32_e32 v79, 0
	v_mov_b32_e32 v80, 0
	v_mov_b32_e32 v81, 0
	v_mov_b32_e32 v82, 0
	v_mov_b32_e32 v83, 0
	v_mov_b32_e32 v84, 0
	v_mov_b32_e32 v85, 0
	v_mov_b32_e32 v86, 0
	v_mov_b32_e32 v87, 0
	v_mov_b32_e32 v88, 0
	v_mov_b32_e32 v89, 0
	v_mov_b32_e32 v90, 0
	v_mov_b32_e32 v91, 0
	v_mov_b32_e32 v92, 0
	v_mov_b32_e32 v93, 0
	v_mov_b32_e32 v94, 0
	v_mov_b32_e32 v95, 0
	v_mov_b32_e32 v96, 0
	v_mov_b32_e32 v97, 0
	v_mov_b32_e32 v98, 0
	v_mov_b32_e32 v99, 0
	v_mov_b32_e32 v100, 0
	v_mov_b32_e32 v101, 0
	v_mov_b32_e32 v102, 0
	v_mov_b32_e32 v103, 0
	v_mov_b32_e32 v104, 0
	v_mov_b32_e32 v105, 0
	v_mov_b32_e32 v106, 0
	v_mov_b32_e32 v107, 0
	v_mov_b32_e32 v108, 0
	v_mov_b32_e32 v109, 0
	v_mov_b32_e32 v110, 0
	v_mov_b32_e32 v111, 0
	v_mov_b32_e32 v112, 0
	v_mov_b32_e32 v113, 0
	v_mov_b32_e32 v114, 0
	v_mov_b32_e32 v115, 0
	v_mov_b32_e32 v116, 0
	v_mov_b32_e32 v117, 0
	v_mov_b32_e32 v118, 0
	v_mov_b32_e32 v119, 0
	v_mov_b32_e32 v120, 0
	v_mov_b32_e32 v121, 0
	v_mov_b32_e32 v122, 0
	v_mov_b32_e32 v123, 0
	v_mov_b32_e32 v124, 0
	v_mov_b32_e32 v125, 0
	v_mov_b32_e32 v126, 0
	v_mov_b32_e32 v127, 0
	s_mov_b32 s31, 0
	s_mov_b32 s30, 24576
	s_waitcnt vmcnt(12)
	s_barrier
	ds_read_b128 v[128:131], v231 offset:0
	ds_read_b128 v[132:135], v231 offset:1024
	ds_read_b128 v[136:139], v231 offset:2048
	ds_read_b128 v[140:143], v231 offset:3072
	ds_read_b128 v[144:147], v230 offset:0
	ds_read_b128 v[148:151], v230 offset:1024
	ds_read_b128 v[152:155], v230 offset:2048
	ds_read_b128 v[156:159], v230 offset:3072
	ds_read_b128 v[160:163], v230 offset:4096
	ds_read_b128 v[164:167], v230 offset:5120
	ds_read_b128 v[168:171], v230 offset:6144
	ds_read_b128 v[172:175], v230 offset:7168

; DI unsigned pack2(float lo, float hi) { const f32x2c v = {lo, hi}; return __builtin_bit_cast(unsigned, __builtin_convertvector(v, bf16x2c)); }
; template <class Epi>
; DI void gemm_tile(char* smem, const bf16_t* __restrict__ A0, int lda0, int ksplit, const bf16_t* __restrict__ A1, int lda1,
;                   const bf16_t* __restrict__ Bt, int K, int row0, int col0, const Epi& epi, int tid) {
;     ...
; #pragma unroll
;   for (int m = 0; m < 8; ++m)
; #pragma unroll
;     for (int n = 0; n < 4; ++n) epi(row0 + wr * 128 + m * 16 + fr, col0 + wc * 64 + n * 16 + fq * 4, acc[m][n]);
; }
; DI void st_bf16x4(bf16_t* o, f32x4 v) { u32x2 q; q.x = pack2(v[0], v[1]); q.y = pack2(v[2], v[3]); *(u32x2*)o = q; }
;   DI void operator()(int row, int col, f32x4 v) const {
;     if (col < n0) st_bf16x4(o0 + (size_t)row * ld0 + col, v);
;     else { const int c = col - n0; if (c < n1) st_bf16x4(o1 + (size_t)row * ld1 + c, v); }
;   }
.Lg11_epi:
	s_nop 7
	s_nop 7
	s_cmpk_ge_u32 s27, 512
	s_cbranch_scc1 .Lg11_eo1
	s_mul_i32 s26, s28, 1024
	s_lshl_b32 s25, s27, 1
	s_add_u32 s26, s26, s25
	s_add_u32 s26, s26, 0x7800000
	s_add_u32 s4, s92, s26
	s_addc_u32 s5, s93, 0
	v_cvt_pk_bf16_f32 v128, v0, v1
	v_cvt_pk_bf16_f32 v129, v2, v3
	ds_write_b64 v236, v[128:129]
	v_cvt_pk_bf16_f32 v130, v4, v5
	v_cvt_pk_bf16_f32 v131, v6, v7
	ds_write_b64 v236, v[130:131] offset:32
	v_cvt_pk_bf16_f32 v132, v8, v9
	v_cvt_pk_bf16_f32 v133, v10, v11
	ds_write_b64 v236, v[132:133] offset:64
	v_cvt_pk_bf16_f32 v134, v12, v13
	v_cvt_pk_bf16_f32 v135, v14, v15
	ds_write_b64 v236, v[134:135] offset:96
	v_cvt_pk_bf16_f32 v136, v16, v17
	v_cvt_pk_bf16_f32 v137, v18, v19
	ds_write_b64 v236, v[136:137] offset:2304
	v_cvt_pk_bf16_f32 v138, v20, v21
	v_cvt_pk_bf16_f32 v139, v22, v23
	ds_write_b64 v236, v[138:139] offset:2336
	v_cvt_pk_bf16_f32 v140, v24, v25
	v_cvt_pk_bf16_f32 v141, v26, v27
	ds_write_b64 v236, v[140:141] offset:2368
	v_cvt_pk_bf16_f32 v142, v28, v29
	v_cvt_pk_bf16_f32 v143, v30, v31
	ds_write_b64 v236, v[142:143] offset:2400
	v_cvt_pk_bf16_f32 v144, v32, v33
	v_cvt_pk_bf16_f32 v145, v34, v35
	ds_write_b64 v236, v[144:145] offset:4608
	v_cvt_pk_bf16_f32 v146, v36, v37
	v_cvt_pk_bf16_f32 v147, v38, v39
	ds_write_b64 v236, v[146:147] offset:4640
	v_cvt_pk_bf16_f32 v148, v40, v41
	v_cvt_pk_bf16_f32 v149, v42, v43
	ds_write_b64 v236, v[148:149] offset:4672
	v_cvt_pk_bf16_f32 v150, v44, v45
	v_cvt_pk_bf16_f32 v151, v46, v47
	ds_write_b64 v236, v[150:151] offset:4704
	v_cvt_pk_bf16_f32 v152, v48, v49
	v_cvt_pk_bf16_f32 v153, v50, v51
	ds_write_b64 v236, v[152:153] offset:6912
	v_cvt_pk_bf16_f32 v154, v52, v53
	v_cvt_pk_bf16_f32 v155, v54, v55
	ds_write_b64 v236, v[154:155] offset:6944
	v_cvt_pk_bf16_f32 v156, v56, v57
	v_cvt_pk_bf16_f32 v157, v58, v59
	ds_write_b64 v236, v[156:157] offset:6976
	v_cvt_pk_bf16_f32 v158, v60, v61
	v_cvt_pk_bf16_f32 v159, v62, v63
	ds_write_b64 v236, v[158:159] offset:7008
	v_cvt_pk_bf16_f32 v128, v64, v65
	v_cvt_pk_bf16_f32 v129, v66, v67
	ds_write_b64 v236, v[128:129] offset:9216
	v_cvt_pk_bf16_f32 v130, v68, v69
	v_cvt_pk_bf16_f32 v131, v70, v71
	ds_write_b64 v236, v[130:131] offset:9248
	v_cvt_pk_bf16_f32 v132, v72, v73
	v_cvt_pk_bf16_f32 v133, v74, v75
	ds_write_b64 v236, v[132:133] offset:9280
	v_cvt_pk_bf16_f32 v134, v76, v77
	v_cvt_pk_bf16_f32 v135, v78, v79
	ds_write_b64 v236, v[134:135] offset:9312
	v_cvt_pk_bf16_f32 v136, v80, v81
	v_cvt_pk_bf16_f32 v137, v82, v83
	ds_write_b64 v236, v[136:137] offset:11520
	v_cvt_pk_bf16_f32 v138, v84, v85
	v_cvt_pk_bf16_f32 v139, v86, v87
	ds_write_b64 v236, v[138:139] offset:11552
	v_cvt_pk_bf16_f32 v140, v88, v89
	v_cvt_pk_bf16_f32 v141, v90, v91
	ds_write_b64 v236, v[140:141] offset:11584
	v_cvt_pk_bf16_f32 v142, v92, v93
	v_cvt_pk_bf16_f32 v143, v94, v95
	ds_write_b64 v236, v[142:143] offset:11616
	v_cvt_pk_bf16_f32 v144, v96, v97
	v_cvt_pk_bf16_f32 v145, v98, v99
	ds_write_b64 v236, v[144:145] offset:13824
	v_cvt_pk_bf16_f32 v146, v100, v101
	v_cvt_pk_bf16_f32 v147, v102, v103
	ds_write_b64 v236, v[146:147] offset:13856
	v_cvt_pk_bf16_f32 v148, v104, v105
	v_cvt_pk_bf16_f32 v149, v106, v107
	ds_write_b64 v236, v[148:149] offset:13888
	v_cvt_pk_bf16_f32 v150, v108, v109
	v_cvt_pk_bf16_f32 v151, v110, v111
	ds_write_b64 v236, v[150:151] offset:13920
	v_cvt_pk_bf16_f32 v152, v112, v113
	v_cvt_pk_bf16_f32 v153, v114, v115
	ds_write_b64 v236, v[152:153] offset:16128
	v_cvt_pk_bf16_f32 v154, v116, v117
	v_cvt_pk_bf16_f32 v155, v118, v119
	ds_write_b64 v236, v[154:155] offset:16160
	v_cvt_pk_bf16_f32 v156, v120, v121
	v_cvt_pk_bf16_f32 v157, v122, v123
	ds_write_b64 v236, v[156:157] offset:16192
	v_cvt_pk_bf16_f32 v158, v124, v125
	v_cvt_pk_bf16_f32 v159, v126, v127
	ds_write_b64 v236, v[158:159] offset:16224
	s_waitcnt lgkmcnt(0)
	ds_read_b128 v[128:131], v237
	ds_read_b128 v[132:135], v237 offset:1152
	ds_read_b128 v[136:139], v237 offset:2304
	ds_read_b128 v[140:143], v237 offset:3456
	ds_read_b128 v[144:147], v237 offset:4608
	ds_read_b128 v[148:151], v237 offset:5760
	ds_read_b128 v[152:155], v237 offset:6912
	ds_read_b128 v[156:159], v237 offset:8064
	ds_read_b128 v[160:163], v237 offset:9216
	ds_read_b128 v[164:167], v237 offset:10368
	ds_read_b128 v[168:171], v237 offset:11520
	ds_read_b128 v[172:175], v237 offset:12672
	ds_read_b128 v[176:179], v237 offset:13824
	ds_read_b128 v[180:183], v237 offset:14976
	ds_read_b128 v[184:187], v237 offset:16128
	ds_read_b128 v[188:191], v237 offset:17280
	s_waitcnt lgkmcnt(15)
	global_store_dwordx4 v238, v[128:131], s[4:5]
	s_add_u32 s4, s4, 0x2000
	s_addc_u32 s5, s5, 0
	s_waitcnt lgkmcnt(14)
	global_store_dwordx4 v238, v[132:135], s[4:5]
	s_add_u32 s4, s4, 0x2000
	s_addc_u32 s5, s5, 0
	s_waitcnt lgkmcnt(13)
	global_store_dwordx4 v238, v[136:139], s[4:5]
	s_add_u32 s4, s4, 0x2000
	s_addc_u32 s5, s5, 0
	s_waitcnt lgkmcnt(12)
	global_store_dwordx4 v238, v[140:143], s[4:5]
	s_add_u32 s4, s4, 0x2000
	s_addc_u32 s5, s5, 0
	s_waitcnt lgkmcnt(11)
	global_store_dwordx4 v238, v[144:147], s[4:5]
	s_add_u32 s4, s4, 0x2000
	s_addc_u32 s5, s5, 0
	s_waitcnt lgkmcnt(10)
	global_store_dwordx4 v238, v[148:151], s[4:5]
	s_add_u32 s4, s4, 0x2000
	s_addc_u32 s5, s5, 0
	s_waitcnt lgkmcnt(9)
	global_store_dwordx4 v238, v[152:155], s[4:5]
	s_add_u32 s4, s4, 0x2000
	s_addc_u32 s5, s5, 0
	s_waitcnt lgkmcnt(8)
	global_store_dwordx4 v238, v[156:159], s[4:5]
	s_add_u32 s4, s4, 0x2000
	s_addc_u32 s5, s5, 0
	s_waitcnt lgkmcnt(7)
	global_store_dwordx4 v238, v[160:163], s[4:5]
	s_add_u32 s4, s4, 0x2000
	s_addc_u32 s5, s5, 0
	s_waitcnt lgkmcnt(6)
	global_store_dwordx4 v238, v[164:167], s[4:5]
	s_add_u32 s4, s4, 0x2000
	s_addc_u32 s5, s5, 0
	s_waitcnt lgkmcnt(5)
	global_store_dwordx4 v238, v[168:171], s[4:5]
	s_add_u32 s4, s4, 0x2000
	s_addc_u32 s5, s5, 0
	s_waitcnt lgkmcnt(4)
	global_store_dwordx4 v238, v[172:175], s[4:5]
	s_add_u32 s4, s4, 0x2000
	s_addc_u32 s5, s5, 0
	s_waitcnt lgkmcnt(3)
	global_store_dwordx4 v238, v[176:179], s[4:5]
	s_add_u32 s4, s4, 0x2000
	s_addc_u32 s5, s5, 0
	s_waitcnt lgkmcnt(2)
	global_store_dwordx4 v238, v[180:183], s[4:5]
	s_add_u32 s4, s4, 0x2000
	s_addc_u32 s5, s5, 0
	s_waitcnt lgkmcnt(1)
	global_store_dwordx4 v238, v[184:187], s[4:5]
	s_add_u32 s4, s4, 0x2000
	s_addc_u32 s5, s5, 0
	s_waitcnt lgkmcnt(0)
	global_store_dwordx4 v238, v[188:191], s[4:5]
	s_nop 1
	s_branch .Lg11_enext
; DI unsigned pack2(float lo, float hi) { const f32x2c v = {lo, hi}; return __builtin_bit_cast(unsigned, __builtin_convertvector(v, bf16x2c)); }
; template <class Epi>
; DI void gemm_tile(char* smem, const bf16_t* __restrict__ A0, int lda0, int ksplit, const bf16_t* __restrict__ A1, int lda1,
;                   const bf16_t* __restrict__ Bt, int K, int row0, int col0, const Epi& epi, int tid) {
;     ...
; #pragma unroll
;   for (int m = 0; m < 8; ++m)
; #pragma unroll
;     for (int n = 0; n < 4; ++n) epi(row0 + wr * 128 + m * 16 + fr, col0 + wc * 64 + n * 16 + fq * 4, acc[m][n]);
; }
; DI void st_bf16x4(bf16_t* o, f32x4 v) { u32x2 q; q.x = pack2(v[0], v[1]); q.y = pack2(v[2], v[3]); *(u32x2*)o = q; }
;   DI void operator()(int row, int col, f32x4 v) const {
;     if (col < n0) st_bf16x4(o0 + (size_t)row * ld0 + col, v);
;     else { const int c = col - n0; if (c < n1) st_bf16x4(o1 + (size_t)row * ld1 + c, v); }
;   }
.Lg11_eo1:
	s_mul_i32 s26, s28, 4160
	s_sub_u32 s25, s27, 512
	s_lshl_b32 s25, s25, 1
	s_add_u32 s26, s26, s25
	s_add_u32 s26, s26, 0x9800000
	s_add_u32 s4, s92, s26
	s_addc_u32 s5, s93, 0
	v_cvt_pk_bf16_f32 v128, v0, v1
	v_cvt_pk_bf16_f32 v129, v2, v3
	ds_write_b64 v236, v[128:129]
	v_cvt_pk_bf16_f32 v130, v4, v5
	v_cvt_pk_bf16_f32 v131, v6, v7
	ds_write_b64 v236, v[130:131] offset:32
	v_cvt_pk_bf16_f32 v132, v8, v9
	v_cvt_pk_bf16_f32 v133, v10, v11
	ds_write_b64 v236, v[132:133] offset:64
	v_cvt_pk_bf16_f32 v134, v12, v13
	v_cvt_pk_bf16_f32 v135, v14, v15
	ds_write_b64 v236, v[134:135] offset:96
	v_cvt_pk_bf16_f32 v136, v16, v17
	v_cvt_pk_bf16_f32 v137, v18, v19
	ds_write_b64 v236, v[136:137] offset:2304
	v_cvt_pk_bf16_f32 v138, v20, v21
	v_cvt_pk_bf16_f32 v139, v22, v23
	ds_write_b64 v236, v[138:139] offset:2336
	v_cvt_pk_bf16_f32 v140, v24, v25
	v_cvt_pk_bf16_f32 v141, v26, v27
	ds_write_b64 v236, v[140:141] offset:2368
	v_cvt_pk_bf16_f32 v142, v28, v29
	v_cvt_pk_bf16_f32 v143, v30, v31
	ds_write_b64 v236, v[142:143] offset:2400
	v_cvt_pk_bf16_f32 v144, v32, v33
	v_cvt_pk_bf16_f32 v145, v34, v35
	ds_write_b64 v236, v[144:145] offset:4608
	v_cvt_pk_bf16_f32 v146, v36, v37
	v_cvt_pk_bf16_f32 v147, v38, v39
	ds_write_b64 v236, v[146:147] offset:4640
	v_cvt_pk_bf16_f32 v148, v40, v41
	v_cvt_pk_bf16_f32 v149, v42, v43
	ds_write_b64 v236, v[148:149] offset:4672
	v_cvt_pk_bf16_f32 v150, v44, v45
	v_cvt_pk_bf16_f32 v151, v46, v47
	ds_write_b64 v236, v[150:151] offset:4704
	v_cvt_pk_bf16_f32 v152, v48, v49
	v_cvt_pk_bf16_f32 v153, v50, v51
	ds_write_b64 v236, v[152:153] offset:6912
	v_cvt_pk_bf16_f32 v154, v52, v53
	v_cvt_pk_bf16_f32 v155, v54, v55
	ds_write_b64 v236, v[154:155] offset:6944
	v_cvt_pk_bf16_f32 v156, v56, v57
	v_cvt_pk_bf16_f32 v157, v58, v59
	ds_write_b64 v236, v[156:157] offset:6976
	v_cvt_pk_bf16_f32 v158, v60, v61
	v_cvt_pk_bf16_f32 v159, v62, v63
	ds_write_b64 v236, v[158:159] offset:7008
	v_cvt_pk_bf16_f32 v128, v64, v65
	v_cvt_pk_bf16_f32 v129, v66, v67
	ds_write_b64 v236, v[128:129] offset:9216
	v_cvt_pk_bf16_f32 v130, v68, v69
	v_cvt_pk_bf16_f32 v131, v70, v71
	ds_write_b64 v236, v[130:131] offset:9248
	v_cvt_pk_bf16_f32 v132, v72, v73
	v_cvt_pk_bf16_f32 v133, v74, v75
	ds_write_b64 v236, v[132:133] offset:9280
	v_cvt_pk_bf16_f32 v134, v76, v77
	v_cvt_pk_bf16_f32 v135, v78, v79
	ds_write_b64 v236, v[134:135] offset:9312
	v_cvt_pk_bf16_f32 v136, v80, v81
	v_cvt_pk_bf16_f32 v137, v82, v83
	ds_write_b64 v236, v[136:137] offset:11520
	v_cvt_pk_bf16_f32 v138, v84, v85
	v_cvt_pk_bf16_f32 v139, v86, v87
	ds_write_b64 v236, v[138:139] offset:11552
	v_cvt_pk_bf16_f32 v140, v88, v89
	v_cvt_pk_bf16_f32 v141, v90, v91
	ds_write_b64 v236, v[140:141] offset:11584
	v_cvt_pk_bf16_f32 v142, v92, v93
	v_cvt_pk_bf16_f32 v143, v94, v95
	ds_write_b64 v236, v[142:143] offset:11616
	v_cvt_pk_bf16_f32 v144, v96, v97
	v_cvt_pk_bf16_f32 v145, v98, v99
	ds_write_b64 v236, v[144:145] offset:13824
	v_cvt_pk_bf16_f32 v146, v100, v101
	v_cvt_pk_bf16_f32 v147, v102, v103
	ds_write_b64 v236, v[146:147] offset:13856
	v_cvt_pk_bf16_f32 v148, v104, v105
	v_cvt_pk_bf16_f32 v149, v106, v107
	ds_write_b64 v236, v[148:149] offset:13888
	v_cvt_pk_bf16_f32 v150, v108, v109
	v_cvt_pk_bf16_f32 v151, v110, v111
	ds_write_b64 v236, v[150:151] offset:13920
	v_cvt_pk_bf16_f32 v152, v112, v113
	v_cvt_pk_bf16_f32 v153, v114, v115
	ds_write_b64 v236, v[152:153] offset:16128
	v_cvt_pk_bf16_f32 v154, v116, v117
	v_cvt_pk_bf16_f32 v155, v118, v119
	ds_write_b64 v236, v[154:155] offset:16160
	v_cvt_pk_bf16_f32 v156, v120, v121
	v_cvt_pk_bf16_f32 v157, v122, v123
	ds_write_b64 v236, v[156:157] offset:16192
	v_cvt_pk_bf16_f32 v158, v124, v125
	v_cvt_pk_bf16_f32 v159, v126, v127
	ds_write_b64 v236, v[158:159] offset:16224
	s_waitcnt lgkmcnt(0)
	ds_read_b128 v[128:131], v237
	ds_read_b128 v[132:135], v237 offset:1152
	ds_read_b128 v[136:139], v237 offset:2304
	ds_read_b128 v[140:143], v237 offset:3456
	ds_read_b128 v[144:147], v237 offset:4608
	ds_read_b128 v[148:151], v237 offset:5760
	ds_read_b128 v[152:155], v237 offset:6912
	ds_read_b128 v[156:159], v237 offset:8064
	ds_read_b128 v[160:163], v237 offset:9216
	ds_read_b128 v[164:167], v237 offset:10368
	ds_read_b128 v[168:171], v237 offset:11520
	ds_read_b128 v[172:175], v237 offset:12672
	ds_read_b128 v[176:179], v237 offset:13824
	ds_read_b128 v[180:183], v237 offset:14976
	ds_read_b128 v[184:187], v237 offset:16128
	ds_read_b128 v[188:191], v237 offset:17280
	s_sub_u32 s25, s27, 512
	s_sub_u32 s25, 2080, s25
	v_cmp_gt_i32_e32 vcc, s25, v248
	s_and_saveexec_b64 s[2:3], vcc
	s_waitcnt lgkmcnt(15)
	global_store_dwordx4 v239, v[128:131], s[4:5]
	s_add_u32 s4, s4, 0x8200
	s_addc_u32 s5, s5, 0
	s_waitcnt lgkmcnt(14)
	global_store_dwordx4 v239, v[132:135], s[4:5]
	s_add_u32 s4, s4, 0x8200
	s_addc_u32 s5, s5, 0
	s_waitcnt lgkmcnt(13)
	global_store_dwordx4 v239, v[136:139], s[4:5]
	s_add_u32 s4, s4, 0x8200
	s_addc_u32 s5, s5, 0
	s_waitcnt lgkmcnt(12)
	global_store_dwordx4 v239, v[140:143], s[4:5]
	s_add_u32 s4, s4, 0x8200
	s_addc_u32 s5, s5, 0
	s_waitcnt lgkmcnt(11)
	global_store_dwordx4 v239, v[144:147], s[4:5]
	s_add_u32 s4, s4, 0x8200
	s_addc_u32 s5, s5, 0
	s_waitcnt lgkmcnt(10)
	global_store_dwordx4 v239, v[148:151], s[4:5]
	s_add_u32 s4, s4, 0x8200
	s_addc_u32 s5, s5, 0
	s_waitcnt lgkmcnt(9)
	global_store_dwordx4 v239, v[152:155], s[4:5]
	s_add_u32 s4, s4, 0x8200
	s_addc_u32 s5, s5, 0
	s_waitcnt lgkmcnt(8)
	global_store_dwordx4 v239, v[156:159], s[4:5]
	s_add_u32 s4, s4, 0x8200
	s_addc_u32 s5, s5, 0
	s_waitcnt lgkmcnt(7)
	global_store_dwordx4 v239, v[160:163], s[4:5]
	s_add_u32 s4, s4, 0x8200
	s_addc_u32 s5, s5, 0
	s_waitcnt lgkmcnt(6)
	global_store_dwordx4 v239, v[164:167], s[4:5]
	s_add_u32 s4, s4, 0x8200
	s_addc_u32 s5, s5, 0
	s_waitcnt lgkmcnt(5)
	global_store_dwordx4 v239, v[168:171], s[4:5]
	s_add_u32 s4, s4, 0x8200
	s_addc_u32 s5, s5, 0
	s_waitcnt lgkmcnt(4)
	global_store_dwordx4 v239, v[172:175], s[4:5]
	s_add_u32 s4, s4, 0x8200
	s_addc_u32 s5, s5, 0
	s_waitcnt lgkmcnt(3)
	global_store_dwordx4 v239, v[176:179], s[4:5]
	s_add_u32 s4, s4, 0x8200
	s_addc_u32 s5, s5, 0
	s_waitcnt lgkmcnt(2)
	global_store_dwordx4 v239, v[180:183], s[4:5]
	s_add_u32 s4, s4, 0x8200
	s_addc_u32 s5, s5, 0
	s_waitcnt lgkmcnt(1)
	global_store_dwordx4 v239, v[184:187], s[4:5]
	s_add_u32 s4, s4, 0x8200
	s_addc_u32 s5, s5, 0
	s_waitcnt lgkmcnt(0)
	global_store_dwordx4 v239, v[188:191], s[4:5]
	s_or_b64 exec, exec, s[2:3]
	s_nop 1

; #define PH(k) case k: if (ONLY_PHASE >= 0 && ONLY_PHASE != k) break;
; template <class Epi>
; DI void gemm_tile(char* smem, const bf16_t* __restrict__ A0, int lda0, int ksplit, const bf16_t* __restrict__ A1, int lda1,
;                   const bf16_t* __restrict__ Bt, int K, int row0, int col0, const Epi& epi, int tid) {
;   constexpr int BK = 32, PITCH = 40, BUF = (256 + 128) * PITCH;
;   bf16_t* sbase = (bf16_t*)smem;
;   const int lane = tid & 63, wid = tid >> 6, wr = wid >> 1, wc = wid & 1, fr = lane & 15, fq = lane >> 4;
;   f32x4 acc[8][4];
; #pragma unroll
;   for (int m = 0; m < 8; ++m)
; #pragma unroll
;     for (int n = 0; n < 4; ++n) acc[m][n] = (f32x4){0.f, 0.f, 0.f, 0.f};
;   u32x4 ra[2][4], rb[2][2];
;   const int nk = K / BK;
;   const int sr = tid >> 2, scv = tid & 3;
; template <int ph> DI void run_phase(const Ctx& c, char* smem) {
;     ...
;     PH(17) gemm_phase(smem, XN, 1024, 1 << 30, XN, 1024, (const bf16_t*)(ws + OFF_W1) + 4096ull * 1024, 1024, 32, EpiRelu2{(bf16_t*)(ws + OFF_R1)}, TIDX); break;
.LBB0_1890:
	s_cmp_gt_i32 s94, 17
	s_cselect_b64 s[0:1], -1, 0
	s_cmp_lt_i32 s95, 18
	s_cselect_b64 s[2:3], -1, 0
	s_or_b64 s[0:1], s[0:1], s[2:3]
	s_and_b64 vcc, exec, s[0:1]
	s_cbranch_vccnz .LBB0_1918
	s_add_u32 s2, s92, 0x3800000
	s_waitcnt lgkmcnt(0)
	s_load_dword s14, s[74:75], 0x180
	s_addc_u32 s3, s93, 0
	s_add_u32 s4, s92, 0x13c0000
	s_addc_u32 s5, s93, 0
	s_add_u32 s0, s92, 0x7800000
	s_addc_u32 s1, s93, 0
	s_and_b32 s16, s72, 0xffffffc0
	v_mbcnt_hi_u32_b32 v195, -1, v194
	s_waitcnt lgkmcnt(0)
	s_and_b32 s15, s14, 7
	s_cmp_lg_u32 s15, 0
	s_waitcnt vmcnt(16)
	v_add_u32_e32 v196, s16, v195
	v_mbcnt_lo_u32_b32 v240, -1, 0
	v_mbcnt_hi_u32_b32 v240, -1, v240
	s_lshr_b32 s12, s72, 6
	s_lshl_b32 s101, s12, 10
	v_and_b32_e32 v241, 15, v240
	v_lshrrev_b32_e32 v242, 4, v240
	v_bfe_u32 v243, v240, 3, 1
	v_mul_u32_u24_e32 v243, 3, v243
	v_xor_b32_e32 v243, v242, v243
	v_lshlrev_b32_e32 v243, 4, v243
	v_lshl_add_u32 v243, v241, 6, v243
	s_lshr_b32 s11, s12, 1
	s_lshl_b32 s11, s11, 13
	v_add_u32_e32 v230, s11, v243
	s_and_b32 s11, s12, 1
	s_lshl_b32 s11, s11, 12
	s_add_u32 s11, s11, 16384
	v_add_u32_e32 v231, s11, v243
	s_lshr_b32 s11, s12, 1
	s_lshl_b32 s11, s11, 7
	v_add_u32_e32 v244, s11, v241
	s_and_b32 s11, s12, 1
	s_lshl_b32 s11, s11, 6
	v_lshl_add_u32 v245, v242, 2, s11
	s_movk_i32 s11, 0x2000
	v_mul_lo_u32 v246, v244, s11
	v_lshl_add_u32 v234, v245, 1, v246
	s_mul_i32 s11, s12, 18432
	v_mul_u32_u24_e32 v246, 144, v241
	v_lshl_add_u32 v246, v242, 3, v246
	v_add_u32_e32 v236, s11, v246
	v_lshrrev_b32_e32 v246, 3, v240
	v_mul_u32_u24_e32 v246, 144, v246
	v_and_b32_e32 v247, 7, v240
	v_lshl_add_u32 v246, v247, 4, v246
	v_add_u32_e32 v237, s11, v246
	s_lshr_b32 s11, s12, 1
	s_lshl_b32 s11, s11, 7
	v_lshrrev_b32_e32 v246, 3, v240
	v_add_u32_e32 v246, s11, v246
	s_and_b32 s11, s12, 1
	s_lshl_b32 s11, s11, 6
	v_lshl_add_u32 v248, v247, 3, s11
	s_movk_i32 s11, 8192
	v_mul_lo_u32 v247, v246, s11
	v_lshl_add_u32 v238, v248, 1, v247
	v_lshrrev_b32_e32 v241, 2, v240
	s_lshl_b32 s11, s12, 4
	v_add_u32_e32 v241, s11, v241
	v_bfe_u32 v242, v240, 5, 1
	v_mul_u32_u24_e32 v242, 3, v242
	v_and_b32_e32 v243, 3, v240
	v_xor_b32_e32 v243, v243, v242
	v_lshlrev_b32_e32 v243, 4, v243
	s_mov_b32 s11, 2048
	v_mad_u32_u24 v224, v241, s11, v243
	v_add_u32_e32 v225, 0x20000, v224
	v_add_u32_e32 v226, 0x40000, v224
	v_add_u32_e32 v227, 0x60000, v224
	s_mov_b32 s11, 2048
	v_mad_u32_u24 v228, v241, s11, v243
	v_add_u32_e32 v229, 0x20000, v228
	s_lshr_b32 s17, s96, 3
	s_and_b32 s20, s96, 7
	s_lshl_b32 s20, s20, 1
	s_waitcnt lgkmcnt(0)
; #define LWRITE(S, buf) do { bf16_t* sA_ = sbase + (buf) * BUF; bf16_t* sB_ = sA_ + 256 * PITCH; \
;     _Pragma("unroll") for (int i_ = 0; i_ < 4; ++i_) *(u32x4*)(sA_ + (sr + i_ * 64) * PITCH + scv * 8) = ra[S][i_]; \
;     _Pragma("unroll") for (int i_ = 0; i_ < 2; ++i_) *(u32x4*)(sB_ + (sr + i_ * 64) * PITCH + scv * 8) = rb[S][i_]; } while (0)
; template <class Epi>
; DI void gemm_tile(char* smem, const bf16_t* __restrict__ A0, int lda0, int ksplit, const bf16_t* __restrict__ A1, int lda1,
;                   const bf16_t* __restrict__ Bt, int K, int row0, int col0, const Epi& epi, int tid) {
;     ...
;   __syncthreads();
;   {
;     const int last = nk - 1;
;     GLOAD(0, 0);
;     __builtin_amdgcn_sched_barrier(0);
;     GLOAD(1, 1);
;     __builtin_amdgcn_sched_barrier(0);
;     LWRITE(0, 0);
;     __builtin_amdgcn_sched_barrier(0);
;     GLOAD(0, (2 < last ? 2 : last));
;     __builtin_amdgcn_sched_barrier(0);
;     __syncthreads();
; template <class Epi>
; DI void gemm_phase(char* smem, const bf16_t* A0, int lda0, int ksplit, const bf16_t* A1, int lda1, const bf16_t* Bt, int K, int nN, const Epi& epi, int tid) {
;     ...
;     const int x = blockIdx.x & 7, l = blockIdx.x >> 3, L = G >> 3, per = 8 * nN, tot = 2 * per;
;     for (int q = l; q < tot; q += L) { const int rgl = q / per, rem = q % per, ct = rem >> 3, rt = (x * 2 + rgl) * 8 + (rem & 7);
;       gemm_tile(smem, A0, lda0, ksplit, A1, lda1, Bt, K, rt * 256, ct * 128, epi, tid); }
.Lg17_tile:
	s_cmpk_ge_u32 s17, 512
	s_cbranch_scc1 .Lg17_done
	s_cmpk_ge_u32 s17, 256
	s_cselect_b32 s12, 1, 0
	s_cselect_b32 s11, 256, 0
	s_sub_u32 s11, s17, s11
	s_and_b32 s18, s11, 7
	s_lshl_b32 s18, s18, 3
	s_bfe_u32 s13, s11, 0x30003
	s_or_b32 s18, s18, s13
	s_andn2_b32 s11, s11, 63
	s_or_b32 s11, s11, s18
	s_add_u32 s12, s12, s20
	s_lshl_b32 s12, s12, 3
	s_and_b32 s18, s11, 7
	s_add_u32 s18, s18, s12
	s_lshl_b32 s18, s18, 8
	s_lshr_b32 s13, s11, 3
	s_lshl_b32 s13, s13, 7
	s_mul_i32 s12, s18, 2048
	s_add_u32 s12, s12, 0x3800000
	s_add_u32 s0, s92, s12
	s_addc_u32 s1, s93, 0
	s_mul_i32 s12, s13, 2048
	s_add_u32 s12, s12, 0x13c0000
	s_add_u32 s2, s92, s12
	s_addc_u32 s3, s93, 0
	s_waitcnt lgkmcnt(0)
	s_barrier
	s_mov_b32 s100, 0
	s_mov_b32 s19, 0
	s_add_u32 s11, s19, s101
	s_add_u32 m0, s11, 0
	s_nop 0
	global_load_lds_dwordx4 v224, s[0:1]
	s_add_u32 m0, s11, 4096
	s_nop 0
	global_load_lds_dwordx4 v225, s[0:1]
	s_add_u32 m0, s11, 8192
	s_nop 0
	global_load_lds_dwordx4 v226, s[0:1]
	s_add_u32 m0, s11, 12288
	s_nop 0
	global_load_lds_dwordx4 v227, s[0:1]
	s_add_u32 m0, s11, 16384
	s_nop 0
	global_load_lds_dwordx4 v228, s[2:3]
	s_add_u32 m0, s11, 20480
	s_nop 0
	global_load_lds_dwordx4 v229, s[2:3]
	s_add_u32 s0, s0, 64
	s_addc_u32 s1, s1, 0
	s_add_u32 s2, s2, 64
	s_addc_u32 s3, s3, 0
	s_add_u32 s100, s100, 1
	s_add_u32 s19, s19, 24576
	s_cmp_eq_u32 s19, 73728
	s_cselect_b32 s19, 0, s19
	s_add_u32 s11, s19, s101
	s_add_u32 m0, s11, 0
	s_nop 0
	global_load_lds_dwordx4 v224, s[0:1]
	s_add_u32 m0, s11, 4096
	s_nop 0
	global_load_lds_dwordx4 v225, s[0:1]
	s_add_u32 m0, s11, 8192
	s_nop 0
	global_load_lds_dwordx4 v226, s[0:1]
	s_add_u32 m0, s11, 12288
	s_nop 0
	global_load_lds_dwordx4 v227, s[0:1]
	s_add_u32 m0, s11, 16384
	s_nop 0
	global_load_lds_dwordx4 v228, s[2:3]
	s_add_u32 m0, s11, 20480
	s_nop 0
	global_load_lds_dwordx4 v229, s[2:3]
	s_add_u32 s0, s0, 64
	s_addc_u32 s1, s1, 0
	s_add_u32 s2, s2, 64
	s_addc_u32 s3, s3, 0
	s_add_u32 s100, s100, 1
	s_add_u32 s19, s19, 24576
	s_cmp_eq_u32 s19, 73728
	s_cselect_b32 s19, 0, s19
	s_add_u32 s11, s19, s101
	s_add_u32 m0, s11, 0
	s_nop 0
	global_load_lds_dwordx4 v224, s[0:1]
	s_add_u32 m0, s11, 4096
	s_nop 0
	global_load_lds_dwordx4 v225, s[0:1]
	s_add_u32 m0, s11, 8192
	s_nop 0
	global_load_lds_dwordx4 v226, s[0:1]
	s_add_u32 m0, s11, 12288
	s_nop 0
	global_load_lds_dwordx4 v227, s[0:1]
	s_add_u32 m0, s11, 16384
	s_nop 0
	global_load_lds_dwordx4 v228, s[2:3]
	s_add_u32 m0, s11, 20480
	s_nop 0
	global_load_lds_dwordx4 v229, s[2:3]
	s_add_u32 s0, s0, 64
	s_addc_u32 s1, s1, 0
	s_add_u32 s2, s2, 64
	s_addc_u32 s3, s3, 0
	s_add_u32 s100, s100, 1
	s_add_u32 s19, s19, 24576
	s_cmp_eq_u32 s19, 73728
	s_cselect_b32 s19, 0, s19
	v_mov_b32_e32 v0, 0
	v_mov_b32_e32 v1, 0
	v_mov_b32_e32 v2, 0
	v_mov_b32_e32 v3, 0
	v_mov_b32_e32 v4, 0
	v_mov_b32_e32 v5, 0
	v_mov_b32_e32 v6, 0
	v_mov_b32_e32 v7, 0
	v_mov_b32_e32 v8, 0
	v_mov_b32_e32 v9, 0
	v_mov_b32_e32 v10, 0
	v_mov_b32_e32 v11, 0
	v_mov_b32_e32 v12, 0
	v_mov_b32_e32 v13, 0
	v_mov_b32_e32 v14, 0
	v_mov_b32_e32 v15, 0
	v_mov_b32_e32 v16, 0
	v_mov_b32_e32 v17, 0
	v_mov_b32_e32 v18, 0
	v_mov_b32_e32 v19, 0
	v_mov_b32_e32 v20, 0
	v_mov_b32_e32 v21, 0
	v_mov_b32_e32 v22, 0
	v_mov_b32_e32 v23, 0
	v_mov_b32_e32 v24, 0
	v_mov_b32_e32 v25, 0
	v_mov_b32_e32 v26, 0
	v_mov_b32_e32 v27, 0
	v_mov_b32_e32 v28, 0
	v_mov_b32_e32 v29, 0
	v_mov_b32_e32 v30, 0
	v_mov_b32_e32 v31, 0
	v_mov_b32_e32 v32, 0
	v_mov_b32_e32 v33, 0
	v_mov_b32_e32 v34, 0
	v_mov_b32_e32 v35, 0
	v_mov_b32_e32 v36, 0
	v_mov_b32_e32 v37, 0
	v_mov_b32_e32 v38, 0
	v_mov_b32_e32 v39, 0
	v_mov_b32_e32 v40, 0
	v_mov_b32_e32 v41, 0
	v_mov_b32_e32 v42, 0
	v_mov_b32_e32 v43, 0
	v_mov_b32_e32 v44, 0
	v_mov_b32_e32 v45, 0
	v_mov_b32_e32 v46, 0
	v_mov_b32_e32 v47, 0
	v_mov_b32_e32 v48, 0
	v_mov_b32_e32 v49, 0
	v_mov_b32_e32 v50, 0
	v_mov_b32_e32 v51, 0
	v_mov_b32_e32 v52, 0
	v_mov_b32_e32 v53, 0
	v_mov_b32_e32 v54, 0
	v_mov_b32_e32 v55, 0
	v_mov_b32_e32 v56, 0
	v_mov_b32_e32 v57, 0
	v_mov_b32_e32 v58, 0
	v_mov_b32_e32 v59, 0
	v_mov_b32_e32 v60, 0
	v_mov_b32_e32 v61, 0
	v_mov_b32_e32 v62, 0
	v_mov_b32_e32 v63, 0
	v_mov_b32_e32 v64, 0
	v_mov_b32_e32 v65, 0
	v_mov_b32_e32 v66, 0
	v_mov_b32_e32 v67, 0
	v_mov_b32_e32 v68, 0
	v_mov_b32_e32 v69, 0
	v_mov_b32_e32 v70, 0
	v_mov_b32_e32 v71, 0
	v_mov_b32_e32 v72, 0
	v_mov_b32_e32 v73, 0
	v_mov_b32_e32 v74, 0
	v_mov_b32_e32 v75, 0
	v_mov_b32_e32 v76, 0
	v_mov_b32_e32 v77, 0
	v_mov_b32_e32 v78, 0
	v_mov_b32_e32 v79, 0
	v_mov_b32_e32 v80, 0
	v_mov_b32_e32 v81, 0
	v_mov_b32_e32 v82, 0
	v_mov_b32_e32 v83, 0
	v_mov_b32_e32 v84, 0
	v_mov_b32_e32 v85, 0
	v_mov_b32_e32 v86, 0
	v_mov_b32_e32 v87, 0
	v_mov_b32_e32 v88, 0
	v_mov_b32_e32 v89, 0
	v_mov_b32_e32 v90, 0
	v_mov_b32_e32 v91, 0
	v_mov_b32_e32 v92, 0
	v_mov_b32_e32 v93, 0
	v_mov_b32_e32 v94, 0
	v_mov_b32_e32 v95, 0
	v_mov_b32_e32 v96, 0
	v_mov_b32_e32 v97, 0
	v_mov_b32_e32 v98, 0
	v_mov_b32_e32 v99, 0
	v_mov_b32_e32 v100, 0
	v_mov_b32_e32 v101, 0
	v_mov_b32_e32 v102, 0
	v_mov_b32_e32 v103, 0
	v_mov_b32_e32 v104, 0
	v_mov_b32_e32 v105, 0
	v_mov_b32_e32 v106, 0
	v_mov_b32_e32 v107, 0
	v_mov_b32_e32 v108, 0
	v_mov_b32_e32 v109, 0
	v_mov_b32_e32 v110, 0
	v_mov_b32_e32 v111, 0
	v_mov_b32_e32 v112, 0
	v_mov_b32_e32 v113, 0
	v_mov_b32_e32 v114, 0
	v_mov_b32_e32 v115, 0
	v_mov_b32_e32 v116, 0
	v_mov_b32_e32 v117, 0
	v_mov_b32_e32 v118, 0
	v_mov_b32_e32 v119, 0
	v_mov_b32_e32 v120, 0
	v_mov_b32_e32 v121, 0
	v_mov_b32_e32 v122, 0
	v_mov_b32_e32 v123, 0
	v_mov_b32_e32 v124, 0
	v_mov_b32_e32 v125, 0
	v_mov_b32_e32 v126, 0
	v_mov_b32_e32 v127, 0
	s_mov_b32 s99, 0
	s_mov_b32 s98, 24576
	s_waitcnt vmcnt(12)
	s_barrier
	ds_read_b128 v[128:131], v231 offset:0
	ds_read_b128 v[132:135], v231 offset:1024
	ds_read_b128 v[136:139], v231 offset:2048
	ds_read_b128 v[140:143], v231 offset:3072
	ds_read_b128 v[144:147], v230 offset:0
	ds_read_b128 v[148:151], v230 offset:1024
	ds_read_b128 v[152:155], v230 offset:2048
	ds_read_b128 v[156:159], v230 offset:3072
	ds_read_b128 v[160:163], v230 offset:4096
	ds_read_b128 v[164:167], v230 offset:5120
	ds_read_b128 v[168:171], v230 offset:6144
	ds_read_b128 v[172:175], v230 offset:7168
